# row exchanges in XCD-local mode: per-wave arrival words and partials kept in that XCD L2 (plain stores, sc1 polls), L1 invalidate kept; fallback unchanged
# speedup vs baseline: 1.0139x; 1.0139x over previous
.LBB0_552:
	v_mov_b32_e32 v1, s88
	ds_read_b32 v1, v1 offset:8
	v_readfirstlane_b32 s32, v0
	s_waitcnt lgkmcnt(0)
	v_readfirstlane_b32 s99, v1
	s_lshr_b32 s32, s32, 6
	v_mov_b32_e32 v1, s88
	ds_read_b32 v1, v1 offset:8
	s_waitcnt lgkmcnt(0)
	v_readfirstlane_b32 s99, v1
	s_add_u32 s6, s28, 0x2a0000
	s_addc_u32 s7, s29, 0
	s_cmp_lt_i32 s30, 8
	s_cselect_b64 s[0:1], -1, 0
	s_cmp_gt_i32 s31, 7
	s_cselect_b64 s[2:3], -1, 0
	s_and_b64 s[10:11], s[0:1], s[2:3]
	s_andn2_b64 vcc, exec, s[10:11]
	s_cbranch_vccnz .LBB0_616
	s_cmpk_lt_i32 s24, 0x200
	s_cselect_b64 s[0:1], -1, 0
	s_cmpk_gt_i32 s24, 0x1ff
	v_readfirstlane_b32 s4, v0
	s_cbranch_scc1 .LBB0_555
	s_ashr_i32 s2, s24, 31
	s_lshr_b32 s2, s2, 29
	s_add_i32 s2, s24, s2
	s_and_b32 s3, s2, -8
	s_sub_i32 s3, s24, s3
	s_lshl_b32 s8, s3, 6
	s_ashr_i32 s2, s2, 3
	s_mul_i32 s5, s3, 0x41
	s_cmp_lt_i32 s3, 0
	s_cselect_b32 s3, s5, s8
	s_add_i32 s2, s3, s2
	s_ashr_i32 s3, s2, 31
	s_lshr_b32 s3, s3, 27
	s_add_i32 s3, s2, s3
	s_ashr_i32 s5, s3, 5
	s_andn2_b32 s3, s3, 31
	s_sub_i32 s2, s2, s3
	s_bfe_i32 s3, s2, 0x80000
	s_bfe_u32 s3, s3, 0x3000c
	s_add_i32 s3, s2, s3
	s_bfe_i32 s8, s3, 0x80000
	s_and_b32 s3, s3, 0xf8
	s_sub_i32 s2, s2, s3
	s_lshl_b32 s5, s5, 3
	s_sext_i32_i16 s8, s8
	s_sext_i32_i8 s2, s2
	s_add_i32 s46, s5, s2
	s_ashr_i32 s26, s8, 3

.LBB0_571:
	v_mbcnt_lo_u32_b32 v242, -1, 0
	v_mbcnt_hi_u32_b32 v242, -1, v242
	s_lshl_b32 s57, s26, 8
	v_ashrrev_i32_e32 v244, 4, v242
	v_and_or_b32 v130, v242, 15, s92
	s_ashr_i32 s82, s46, 4
	v_lshlrev_b32_e32 v243, 3, v244
	s_or_b32 s0, s57, s93
	v_lshl_add_u32 v176, s46, 8, v130
	v_add_u32_e32 v130, s0, v243
	s_mul_hi_i32 s1, s82, 0x2c00
	s_mul_i32 s0, s82, 0x2c00
	s_lshl_b32 s84, s26, 2
	s_ashr_i32 s85, s84, 31
	s_lshl_b64 s[80:81], s[0:1], 2
	v_readlane_b32 s0, v254, 15
	s_add_u32 s0, s0, s80
	v_readlane_b32 s1, v254, 31
	s_addc_u32 s1, s1, s81
	v_readlane_b32 s34, v255, 2
	v_ashrrev_i32_e32 v131, 31, v130
	s_add_u32 s78, s34, s80
	v_readlane_b32 s34, v255, 3
	v_readlane_b32 s60, v254, 41
	s_addc_u32 s79, s34, s81
	v_lshlrev_b64 v[146:147], 2, v[130:131]
	v_readlane_b32 s70, v254, 51
	v_readlane_b32 s71, v254, 52
	v_lshlrev_b32_e32 v132, 1, v130
	v_lshl_add_u64 v[154:155], s[0:1], 0, v[146:147]
	v_lshl_add_u64 v[156:157], s[70:71], 0, v[146:147]
	v_lshl_add_u64 v[158:159], s[78:79], 0, v[146:147]
	v_lshl_add_u32 v200, v176, 11, v132
	global_load_dwordx4 v[138:141], v[154:155], off offset:16
	global_load_dwordx4 v[142:145], v[154:155], off
	global_load_dwordx4 v[130:133], v[156:157], off offset:16
	global_load_dwordx4 v[134:137], v[156:157], off
	global_load_dwordx4 v[146:149], v[158:159], off offset:16
	global_load_dwordx4 v[150:153], v[158:159], off
	v_add_u32_e32 v181, 0x8000, v200
	v_add_u32_e32 v180, 0x10000, v200
	v_add_u32_e32 v179, 0x18000, v200
	v_add_u32_e32 v178, 0x40000, v200
	v_add_u32_e32 v173, 0x48000, v200
	v_add_u32_e32 v172, 0x50000, v200
	v_add_u32_e32 v253, 0x58000, v200
	v_add_u32_e32 v252, 0x100, v200
	v_add_u32_e32 v251, 0x8100, v200
	v_add_u32_e32 v250, 0x10100, v200
	v_add_u32_e32 v249, 0x18100, v200
	v_add_u32_e32 v248, 0x40100, v200
	v_add_u32_e32 v247, 0x48100, v200
	v_add_u32_e32 v246, 0x50100, v200
	v_add_u32_e32 v245, 0x58100, v200
	v_ashrrev_i32_e32 v177, 31, v176
	v_cmp_gt_u32_e32 vcc, 16, v242
	v_readlane_b32 s61, v254, 42
	v_readlane_b32 s62, v254, 43
	v_readlane_b32 s63, v254, 44
	v_readlane_b32 s64, v254, 45
	v_readlane_b32 s65, v254, 46
	v_readlane_b32 s66, v254, 47
	v_readlane_b32 s67, v254, 48
	v_readlane_b32 s68, v254, 49
	v_readlane_b32 s69, v254, 50
	v_readlane_b32 s72, v254, 53
	v_readlane_b32 s73, v254, 54
	v_readlane_b32 s74, v254, 55
	v_readlane_b32 s75, v254, 56
	s_waitcnt vmcnt(0)
	v_pk_add_f32 v[152:153], v[152:153], 1.0 op_sel_hi:[1,0]
	v_pk_add_f32 v[150:151], v[150:151], 1.0 op_sel_hi:[1,0]
	v_pk_mul_f32 v[232:233], v[136:137], v[152:153]
	v_pk_mul_f32 v[234:235], v[134:135], v[150:151]
	v_pk_add_f32 v[134:135], v[148:149], 1.0 op_sel_hi:[1,0]
	v_pk_add_f32 v[136:137], v[146:147], 1.0 op_sel_hi:[1,0]
	v_pk_mul_f32 v[228:229], v[132:133], v[134:135]
	v_pk_mul_f32 v[230:231], v[130:131], v[136:137]
	global_load_dwordx4 v[130:133], v[154:155], off offset:528
	global_load_dwordx4 v[134:137], v[154:155], off offset:512
	global_load_dwordx4 v[146:149], v[156:157], off offset:528
	global_load_dwordx4 v[150:153], v[156:157], off offset:512
	s_nop 0
	global_load_dwordx4 v[154:157], v[158:159], off offset:528
	s_nop 0
	global_load_dwordx4 v[158:161], v[158:159], off offset:512
	s_waitcnt vmcnt(0)
	v_pk_add_f32 v[160:161], v[160:161], 1.0 op_sel_hi:[1,0]
	v_pk_add_f32 v[158:159], v[158:159], 1.0 op_sel_hi:[1,0]
	v_pk_mul_f32 v[224:225], v[152:153], v[160:161]
	v_pk_mul_f32 v[226:227], v[150:151], v[158:159]
	v_pk_add_f32 v[150:151], v[156:157], 1.0 op_sel_hi:[1,0]
	v_pk_add_f32 v[152:153], v[154:155], 1.0 op_sel_hi:[1,0]
	v_pk_mul_f32 v[220:221], v[148:149], v[150:151]
	v_pk_mul_f32 v[222:223], v[146:147], v[152:153]
	global_load_dwordx4 v[182:185], v200, s[38:39] nt
	global_load_dwordx4 v[186:189], v181, s[38:39] nt
	global_load_dwordx4 v[190:193], v180, s[38:39] nt
	global_load_dwordx4 v[194:197], v179, s[38:39] nt
	global_load_dwordx4 v[162:165], v178, s[38:39] nt
	global_load_dwordx4 v[158:161], v173, s[38:39] nt
	global_load_dwordx4 v[154:157], v172, s[38:39] nt
	global_load_dwordx4 v[150:153], v253, s[38:39] nt
	global_load_dwordx4 v[146:149], v252, s[38:39] nt
	s_waitcnt vmcnt(8)
	v_lshlrev_b32_e32 v198, 16, v182
	v_and_b32_e32 v199, 0xffff0000, v182
	v_lshlrev_b32_e32 v174, 16, v183
	v_and_b32_e32 v175, 0xffff0000, v183
	v_lshlrev_b32_e32 v182, 16, v184
	v_and_b32_e32 v183, 0xffff0000, v184
	v_lshlrev_b32_e32 v184, 16, v185
	v_and_b32_e32 v185, 0xffff0000, v185
	v_pk_fma_f32 v[174:175], v[128:129], v[144:145], v[174:175]
	v_pk_fma_f32 v[202:203], v[126:127], v[142:143], v[198:199]
	v_pk_fma_f32 v[212:213], v[122:123], v[138:139], v[182:183]
	v_cvt_pk_bf16_f32 v122, v202, v203
	v_cvt_pk_bf16_f32 v123, v174, v175
	v_pk_fma_f32 v[208:209], v[124:125], v[140:141], v[184:185]
	v_cvt_pk_bf16_f32 v124, v212, v213
	v_pk_mul_f32 v[128:129], v[230:231], v[212:213]
	v_cvt_pk_bf16_f32 v125, v208, v209
	global_store_dwordx4 v200, v[122:125], s[38:39]
	v_pk_mul_f32 v[126:127], v[228:229], v[208:209]
	s_waitcnt vmcnt(8)
	v_lshlrev_b32_e32 v182, 16, v188
	v_mul_f32_e32 v122, v203, v203
	v_mul_f32_e32 v123, v175, v175
	v_fmac_f32_e32 v122, v202, v202
	v_fmac_f32_e32 v123, v174, v174
	v_add_f32_e32 v122, v122, v123
	v_mul_f32_e32 v123, v213, v213
	v_fmac_f32_e32 v123, v212, v212
	v_add_f32_e32 v122, v123, v122
	v_mul_f32_e32 v123, v209, v209
	v_fmac_f32_e32 v123, v208, v208
	v_add_f32_e32 v218, v123, v122
	v_pk_mul_f32 v[122:123], v[232:233], v[174:175]
	v_pk_mul_f32 v[124:125], v[234:235], v[202:203]
	v_max_f32_e64 v122, |v122|, |v123|
	v_max_f32_e64 v123, |v126|, |v127|
	v_max_f32_e64 v124, |v124|, |v125|
	v_max3_f32 v123, |v128|, |v129|, v123
	v_max3_f32 v219, v124, v122, v123
	global_load_dwordx4 v[122:125], v251, s[38:39] nt
	v_lshlrev_b32_e32 v126, 16, v186
	v_and_b32_e32 v127, 0xffff0000, v186
	v_lshlrev_b32_e32 v128, 16, v187
	v_and_b32_e32 v129, 0xffff0000, v187
	v_and_b32_e32 v183, 0xffff0000, v188
	v_lshlrev_b32_e32 v184, 16, v189
	v_and_b32_e32 v185, 0xffff0000, v189
	v_pk_fma_f32 v[214:215], v[120:121], v[144:145], v[128:129]
	v_pk_fma_f32 v[216:217], v[118:119], v[142:143], v[126:127]
	v_pk_fma_f32 v[206:207], v[116:117], v[140:141], v[184:185]
	v_pk_fma_f32 v[210:211], v[114:115], v[138:139], v[182:183]
	v_cvt_pk_bf16_f32 v114, v216, v217
	v_cvt_pk_bf16_f32 v115, v214, v215
	s_waitcnt vmcnt(8)
	v_lshlrev_b32_e32 v118, 16, v190
	v_cvt_pk_bf16_f32 v116, v210, v211
	v_cvt_pk_bf16_f32 v117, v206, v207
	global_store_dwordx4 v181, v[114:117], s[38:39]
	global_load_dwordx4 v[114:117], v250, s[38:39] nt
	v_and_b32_e32 v119, 0xffff0000, v190
	v_lshlrev_b32_e32 v120, 16, v191
	v_and_b32_e32 v121, 0xffff0000, v191
	v_lshlrev_b32_e32 v126, 16, v192
	v_and_b32_e32 v127, 0xffff0000, v192
	v_lshlrev_b32_e32 v128, 16, v193
	v_and_b32_e32 v129, 0xffff0000, v193
	v_pk_fma_f32 v[200:201], v[112:113], v[144:145], v[120:121]
	v_pk_fma_f32 v[204:205], v[110:111], v[142:143], v[118:119]
	v_pk_fma_f32 v[192:193], v[108:109], v[140:141], v[128:129]
	v_pk_fma_f32 v[198:199], v[106:107], v[138:139], v[126:127]
	v_cvt_pk_bf16_f32 v106, v204, v205
	v_cvt_pk_bf16_f32 v107, v200, v201
	s_waitcnt vmcnt(9)
	v_lshlrev_b32_e32 v110, 16, v194
	v_cvt_pk_bf16_f32 v108, v198, v199
	v_cvt_pk_bf16_f32 v109, v192, v193
	global_store_dwordx4 v180, v[106:109], s[38:39]
	global_load_dwordx4 v[106:109], v249, s[38:39] nt
	v_and_b32_e32 v111, 0xffff0000, v194
	v_lshlrev_b32_e32 v112, 16, v195
	v_and_b32_e32 v113, 0xffff0000, v195
	v_lshlrev_b32_e32 v118, 16, v196
	v_and_b32_e32 v119, 0xffff0000, v196
	v_lshlrev_b32_e32 v120, 16, v197
	v_and_b32_e32 v121, 0xffff0000, v197
	v_pk_fma_f32 v[190:191], v[104:105], v[144:145], v[112:113]
	v_pk_fma_f32 v[194:195], v[102:103], v[142:143], v[110:111]
	v_pk_fma_f32 v[186:187], v[100:101], v[140:141], v[120:121]
	v_pk_fma_f32 v[188:189], v[98:99], v[138:139], v[118:119]
	v_cvt_pk_bf16_f32 v98, v194, v195
	v_cvt_pk_bf16_f32 v99, v190, v191
	s_waitcnt vmcnt(10)
	v_lshlrev_b32_e32 v102, 16, v162
	v_cvt_pk_bf16_f32 v100, v188, v189
	v_cvt_pk_bf16_f32 v101, v186, v187
	global_store_dwordx4 v179, v[98:101], s[38:39]
	global_load_dwordx4 v[98:101], v248, s[38:39] nt
	v_and_b32_e32 v103, 0xffff0000, v162
	v_lshlrev_b32_e32 v104, 16, v163
	v_and_b32_e32 v105, 0xffff0000, v163
	v_lshlrev_b32_e32 v110, 16, v164
	v_and_b32_e32 v111, 0xffff0000, v164
	v_lshlrev_b32_e32 v112, 16, v165
	v_and_b32_e32 v113, 0xffff0000, v165
	v_pk_fma_f32 v[182:183], v[96:97], v[144:145], v[104:105]
	v_pk_fma_f32 v[184:185], v[94:95], v[142:143], v[102:103]
	v_pk_fma_f32 v[164:165], v[92:93], v[140:141], v[112:113]
	v_pk_fma_f32 v[180:181], v[90:91], v[138:139], v[110:111]
	v_cvt_pk_bf16_f32 v90, v184, v185
	v_cvt_pk_bf16_f32 v91, v182, v183
	s_waitcnt vmcnt(11)
	v_lshlrev_b32_e32 v94, 16, v158
	v_cvt_pk_bf16_f32 v92, v180, v181
	v_cvt_pk_bf16_f32 v93, v164, v165
	global_store_dwordx4 v178, v[90:93], s[38:39]
	global_load_dwordx4 v[90:93], v247, s[38:39] nt
	v_and_b32_e32 v95, 0xffff0000, v158
	v_lshlrev_b32_e32 v96, 16, v159
	v_and_b32_e32 v97, 0xffff0000, v159
	v_lshlrev_b32_e32 v102, 16, v160
	v_and_b32_e32 v103, 0xffff0000, v160
	v_lshlrev_b32_e32 v104, 16, v161
	v_and_b32_e32 v105, 0xffff0000, v161
	v_pk_fma_f32 v[162:163], v[88:89], v[144:145], v[96:97]
	v_pk_fma_f32 v[178:179], v[86:87], v[142:143], v[94:95]
	v_pk_fma_f32 v[158:159], v[84:85], v[140:141], v[104:105]
	v_pk_fma_f32 v[160:161], v[82:83], v[138:139], v[102:103]
	v_cvt_pk_bf16_f32 v82, v178, v179
	v_cvt_pk_bf16_f32 v83, v162, v163
	s_waitcnt vmcnt(12)
	v_lshlrev_b32_e32 v86, 16, v154
	v_cvt_pk_bf16_f32 v84, v160, v161
	v_cvt_pk_bf16_f32 v85, v158, v159
	global_store_dwordx4 v173, v[82:85], s[38:39]
	global_load_dwordx4 v[82:85], v246, s[38:39] nt
	v_and_b32_e32 v87, 0xffff0000, v154
	v_lshlrev_b32_e32 v88, 16, v155
	v_and_b32_e32 v89, 0xffff0000, v155
	v_lshlrev_b32_e32 v94, 16, v156
	v_and_b32_e32 v95, 0xffff0000, v156
	v_lshlrev_b32_e32 v96, 16, v157
	v_and_b32_e32 v97, 0xffff0000, v157
	v_pk_fma_f32 v[154:155], v[80:81], v[144:145], v[88:89]
	v_pk_fma_f32 v[156:157], v[78:79], v[142:143], v[86:87]
	v_pk_fma_f32 v[120:121], v[76:77], v[140:141], v[96:97]
	v_pk_fma_f32 v[128:129], v[74:75], v[138:139], v[94:95]
	v_cvt_pk_bf16_f32 v74, v156, v157
	v_cvt_pk_bf16_f32 v75, v154, v155
	s_waitcnt vmcnt(13)
	v_lshlrev_b32_e32 v78, 16, v150
	v_cvt_pk_bf16_f32 v76, v128, v129
	v_cvt_pk_bf16_f32 v77, v120, v121
	global_store_dwordx4 v172, v[74:77], s[38:39]
	global_load_dwordx4 v[74:77], v245, s[38:39] nt
	v_and_b32_e32 v79, 0xffff0000, v150
	v_lshlrev_b32_e32 v80, 16, v151
	v_and_b32_e32 v81, 0xffff0000, v151
	v_lshlrev_b32_e32 v86, 16, v152
	v_and_b32_e32 v87, 0xffff0000, v152
	v_lshlrev_b32_e32 v88, 16, v153
	v_and_b32_e32 v89, 0xffff0000, v153
	v_pk_fma_f32 v[118:119], v[68:69], v[144:145], v[80:81]
	v_pk_fma_f32 v[126:127], v[66:67], v[142:143], v[78:79]
	v_pk_fma_f32 v[110:111], v[60:61], v[140:141], v[88:89]
	v_pk_fma_f32 v[112:113], v[58:59], v[138:139], v[86:87]
	v_cvt_pk_bf16_f32 v58, v126, v127
	v_cvt_pk_bf16_f32 v59, v118, v119
	s_waitcnt vmcnt(14)
	v_lshlrev_b32_e32 v66, 16, v148
	v_cvt_pk_bf16_f32 v60, v112, v113
	v_cvt_pk_bf16_f32 v61, v110, v111
	global_store_dwordx4 v253, v[58:61], s[38:39]
	v_and_b32_e32 v67, 0xffff0000, v148
	v_lshlrev_b32_e32 v68, 16, v149
	v_lshlrev_b32_e32 v58, 16, v146
	v_and_b32_e32 v59, 0xffff0000, v146
	v_lshlrev_b32_e32 v60, 16, v147
	v_and_b32_e32 v61, 0xffff0000, v147
	v_and_b32_e32 v69, 0xffff0000, v149
	v_pk_fma_f32 v[94:95], v[72:73], v[136:137], v[60:61]
	v_pk_fma_f32 v[104:105], v[70:71], v[134:135], v[58:59]
	v_pk_fma_f32 v[72:73], v[64:65], v[132:133], v[68:69]
	v_cvt_pk_bf16_f32 v58, v104, v105
	v_cvt_pk_bf16_f32 v59, v94, v95
	v_pk_fma_f32 v[88:89], v[62:63], v[130:131], v[66:67]
	v_pk_mul_f32 v[62:63], v[220:221], v[72:73]
	v_cvt_pk_bf16_f32 v60, v88, v89
	v_cvt_pk_bf16_f32 v61, v72, v73
	global_store_dwordx4 v252, v[58:61], s[38:39]
	v_pk_mul_f32 v[64:65], v[222:223], v[88:89]
	s_nop 0
	v_mul_f32_e32 v58, v105, v105
	v_mul_f32_e32 v59, v95, v95
	v_fmac_f32_e32 v58, v104, v104
	v_fmac_f32_e32 v59, v94, v94
	v_add_f32_e32 v58, v58, v59
	v_mul_f32_e32 v59, v89, v89
	v_fmac_f32_e32 v59, v88, v88
	v_add_f32_e32 v58, v59, v58
	v_mul_f32_e32 v59, v73, v73
	v_fmac_f32_e32 v59, v72, v72
	v_add_f32_e32 v58, v59, v58
	v_add_f32_e32 v138, v218, v58
	v_pk_mul_f32 v[58:59], v[224:225], v[94:95]
	v_pk_mul_f32 v[60:61], v[226:227], v[104:105]
	v_max_f32_e64 v58, |v58|, |v59|
	v_max_f32_e64 v59, |v62|, |v63|
	v_max_f32_e64 v60, |v60|, |v61|
	v_max3_f32 v59, |v64|, |v65|, v59
	v_max3_f32 v58, v60, v58, v59
	v_max3_f32 v139, v219, 0, v58
	s_waitcnt vmcnt(14)
	v_lshlrev_b32_e32 v58, 16, v122
	v_and_b32_e32 v59, 0xffff0000, v122
	v_lshlrev_b32_e32 v60, 16, v123
	v_and_b32_e32 v61, 0xffff0000, v123
	v_lshlrev_b32_e32 v62, 16, v124
	v_and_b32_e32 v63, 0xffff0000, v124
	v_lshlrev_b32_e32 v64, 16, v125
	v_and_b32_e32 v65, 0xffff0000, v125
	v_pk_fma_f32 v[96:97], v[56:57], v[136:137], v[60:61]
	v_pk_fma_f32 v[102:103], v[54:55], v[134:135], v[58:59]
	v_pk_fma_f32 v[80:81], v[52:53], v[132:133], v[64:65]
	v_pk_fma_f32 v[86:87], v[50:51], v[130:131], v[62:63]
	v_cvt_pk_bf16_f32 v50, v102, v103
	v_cvt_pk_bf16_f32 v51, v96, v97
	s_waitcnt vmcnt(12)
	v_lshlrev_b32_e32 v54, 16, v116
	v_cvt_pk_bf16_f32 v52, v86, v87
	v_cvt_pk_bf16_f32 v53, v80, v81
	global_store_dwordx4 v251, v[50:53], s[38:39]
	v_and_b32_e32 v55, 0xffff0000, v116
	v_lshlrev_b32_e32 v56, 16, v117
	v_lshlrev_b32_e32 v50, 16, v114
	v_and_b32_e32 v51, 0xffff0000, v114
	v_lshlrev_b32_e32 v52, 16, v115
	v_and_b32_e32 v53, 0xffff0000, v115
	v_and_b32_e32 v57, 0xffff0000, v117
	v_pk_fma_f32 v[70:71], v[48:49], v[136:137], v[52:53]
	v_pk_fma_f32 v[78:79], v[46:47], v[134:135], v[50:51]
	v_pk_fma_f32 v[64:65], v[44:45], v[132:133], v[56:57]
	v_pk_fma_f32 v[68:69], v[42:43], v[130:131], v[54:55]
	v_cvt_pk_bf16_f32 v42, v78, v79
	v_cvt_pk_bf16_f32 v43, v70, v71
	s_waitcnt vmcnt(11)
	v_lshlrev_b32_e32 v46, 16, v108
	v_cvt_pk_bf16_f32 v44, v68, v69
	v_cvt_pk_bf16_f32 v45, v64, v65
	global_store_dwordx4 v250, v[42:45], s[38:39]
	v_and_b32_e32 v47, 0xffff0000, v108
	v_lshlrev_b32_e32 v48, 16, v109
	v_lshlrev_b32_e32 v42, 16, v106
	v_and_b32_e32 v43, 0xffff0000, v106
	v_lshlrev_b32_e32 v44, 16, v107
	v_and_b32_e32 v45, 0xffff0000, v107
	v_and_b32_e32 v49, 0xffff0000, v109
	v_pk_fma_f32 v[62:63], v[40:41], v[136:137], v[44:45]
	v_pk_fma_f32 v[66:67], v[38:39], v[134:135], v[42:43]
	v_pk_fma_f32 v[58:59], v[36:37], v[132:133], v[48:49]
	v_pk_fma_f32 v[60:61], v[34:35], v[130:131], v[46:47]
	v_cvt_pk_bf16_f32 v34, v66, v67
	v_cvt_pk_bf16_f32 v35, v62, v63
	s_waitcnt vmcnt(10)
	v_lshlrev_b32_e32 v38, 16, v100
	v_cvt_pk_bf16_f32 v36, v60, v61
	v_cvt_pk_bf16_f32 v37, v58, v59
	global_store_dwordx4 v249, v[34:37], s[38:39]
	v_and_b32_e32 v39, 0xffff0000, v100
	v_lshlrev_b32_e32 v40, 16, v101
	v_lshlrev_b32_e32 v34, 16, v98
	v_and_b32_e32 v35, 0xffff0000, v98
	v_lshlrev_b32_e32 v36, 16, v99
	v_and_b32_e32 v37, 0xffff0000, v99
	v_and_b32_e32 v41, 0xffff0000, v101
	v_pk_fma_f32 v[54:55], v[32:33], v[136:137], v[36:37]
	v_pk_fma_f32 v[56:57], v[30:31], v[134:135], v[34:35]
	v_pk_fma_f32 v[48:49], v[28:29], v[132:133], v[40:41]
	v_pk_fma_f32 v[52:53], v[26:27], v[130:131], v[38:39]
	v_cvt_pk_bf16_f32 v26, v56, v57
	v_cvt_pk_bf16_f32 v27, v54, v55
	s_waitcnt vmcnt(9)
	v_lshlrev_b32_e32 v30, 16, v92
	v_cvt_pk_bf16_f32 v28, v52, v53
	v_cvt_pk_bf16_f32 v29, v48, v49
	global_store_dwordx4 v248, v[26:29], s[38:39]
	v_and_b32_e32 v31, 0xffff0000, v92
	v_lshlrev_b32_e32 v32, 16, v93
	v_lshlrev_b32_e32 v26, 16, v90
	v_and_b32_e32 v27, 0xffff0000, v90
	v_lshlrev_b32_e32 v28, 16, v91
	v_and_b32_e32 v29, 0xffff0000, v91
	v_and_b32_e32 v33, 0xffff0000, v93
	v_pk_fma_f32 v[46:47], v[24:25], v[136:137], v[28:29]
	v_pk_fma_f32 v[50:51], v[22:23], v[134:135], v[26:27]
	v_pk_fma_f32 v[42:43], v[20:21], v[132:133], v[32:33]
	v_pk_fma_f32 v[44:45], v[18:19], v[130:131], v[30:31]
	v_cvt_pk_bf16_f32 v18, v50, v51
	v_cvt_pk_bf16_f32 v19, v46, v47
	s_waitcnt vmcnt(8)
	v_lshlrev_b32_e32 v22, 16, v84
	v_cvt_pk_bf16_f32 v20, v44, v45
	v_cvt_pk_bf16_f32 v21, v42, v43
	global_store_dwordx4 v247, v[18:21], s[38:39]
	v_and_b32_e32 v23, 0xffff0000, v84
	v_lshlrev_b32_e32 v24, 16, v85
	v_lshlrev_b32_e32 v18, 16, v82
	v_and_b32_e32 v19, 0xffff0000, v82
	v_lshlrev_b32_e32 v20, 16, v83
	v_and_b32_e32 v21, 0xffff0000, v83
	v_and_b32_e32 v25, 0xffff0000, v85
	v_pk_fma_f32 v[38:39], v[16:17], v[136:137], v[20:21]
	v_pk_fma_f32 v[40:41], v[14:15], v[134:135], v[18:19]
	v_pk_fma_f32 v[32:33], v[12:13], v[132:133], v[24:25]
	v_pk_fma_f32 v[36:37], v[10:11], v[130:131], v[22:23]
	v_cvt_pk_bf16_f32 v10, v40, v41
	v_cvt_pk_bf16_f32 v11, v38, v39
	s_waitcnt vmcnt(7)
	v_lshlrev_b32_e32 v14, 16, v76
	v_cvt_pk_bf16_f32 v12, v36, v37
	v_cvt_pk_bf16_f32 v13, v32, v33
	global_store_dwordx4 v246, v[10:13], s[38:39]
	v_and_b32_e32 v15, 0xffff0000, v76
	v_lshlrev_b32_e32 v16, 16, v77
	v_lshlrev_b32_e32 v10, 16, v74
	v_and_b32_e32 v11, 0xffff0000, v74
	v_lshlrev_b32_e32 v12, 16, v75
	v_and_b32_e32 v13, 0xffff0000, v75
	v_and_b32_e32 v17, 0xffff0000, v77
	v_pk_fma_f32 v[30:31], v[8:9], v[136:137], v[12:13]
	v_pk_fma_f32 v[34:35], v[6:7], v[134:135], v[10:11]
	v_pk_fma_f32 v[28:29], v[2:3], v[130:131], v[14:15]
	v_cvt_pk_bf16_f32 v2, v34, v35
	v_cvt_pk_bf16_f32 v3, v30, v31
	v_pk_fma_f32 v[26:27], v[4:5], v[132:133], v[16:17]
	v_cvt_pk_bf16_f32 v4, v28, v29
	v_lshlrev_b64 v[18:19], 7, v[176:177]
	v_cvt_pk_bf16_f32 v5, v26, v27
	global_store_dwordx4 v245, v[2:5], s[38:39]
	s_nop 1
	v_and_b32_e32 v3, 64, v239
	v_xor_b32_e32 v2, 16, v239
	v_add_u32_e32 v3, 64, v3
	v_cmp_lt_i32_e64 s[0:1], v2, v3
	s_nop 1
	v_cndmask_b32_e64 v2, v239, v2, s[0:1]
	v_lshlrev_b32_e32 v122, 2, v2
	v_xor_b32_e32 v2, 32, v239
	v_cmp_lt_i32_e64 s[0:1], v2, v3
	ds_bpermute_b32 v4, v122, v139
	s_waitcnt lgkmcnt(0)
	v_max_f32_e32 v4, v4, v4
	v_cndmask_b32_e64 v2, v239, v2, s[0:1]
	v_lshlrev_b32_e32 v123, 2, v2
	ds_bpermute_b32 v2, v122, v138
	v_max_f32_e32 v4, v139, v4
	ds_bpermute_b32 v5, v123, v4
	s_waitcnt lgkmcnt(1)
	v_add_f32_e32 v2, v138, v2
	ds_bpermute_b32 v3, v123, v2
	s_and_saveexec_b64 s[0:1], vcc
	s_cbranch_execz .LBB0_573
	s_waitcnt lgkmcnt(1)
	v_max_f32_e32 v5, v5, v5
	v_max_f32_e32 v4, v4, v4
	v_max_f32_e32 v5, v4, v5
	s_waitcnt lgkmcnt(0)
	v_add_f32_e32 v4, v2, v3
	v_lshl_add_u64 v[2:3], s[42:43], 0, v[18:19]
	v_lshl_add_u64 v[2:3], s[84:85], 3, v[2:3]
	s_lshl_b32 s40, s91, 3
	v_lshl_add_u64 v[2:3], v[2:3], 0, s[40:41]
	s_cmp_eq_u32 s99, 1
	s_cbranch_scc1 .Lxp_plain_1
	global_store_dwordx2 v[2:3], v[4:5], off sc1
	s_branch .Lxp_done_1
.Lxp_plain_1:
	global_store_dwordx2 v[2:3], v[4:5], off
.Lxp_done_1:
.LBB0_573:
	s_or_b64 exec, exec, s[0:1]
	v_mul_f32_e32 v2, v217, v217
	s_waitcnt lgkmcnt(0)
	v_mul_f32_e32 v3, v215, v215
	v_fmac_f32_e32 v2, v216, v216
	v_fmac_f32_e32 v3, v214, v214
	v_add_f32_e32 v2, v2, v3
	v_mul_f32_e32 v3, v211, v211
	v_fmac_f32_e32 v3, v210, v210
	v_add_f32_e32 v2, v3, v2
	v_mul_f32_e32 v3, v207, v207
	v_fmac_f32_e32 v3, v206, v206
	v_add_f32_e32 v10, v3, v2
	v_pk_mul_f32 v[2:3], v[232:233], v[214:215]
	v_pk_mul_f32 v[6:7], v[228:229], v[206:207]
	v_pk_mul_f32 v[4:5], v[234:235], v[216:217]
	v_pk_mul_f32 v[8:9], v[230:231], v[210:211]
	v_max_f32_e64 v2, |v2|, |v3|
	v_max_f32_e64 v3, |v6|, |v7|
	v_max_f32_e64 v4, |v4|, |v5|
	v_max3_f32 v3, |v8|, |v9|, v3
	v_max3_f32 v11, v4, v2, v3
	v_mul_f32_e32 v2, v103, v103
	v_mul_f32_e32 v3, v97, v97
	v_fmac_f32_e32 v2, v102, v102
	v_fmac_f32_e32 v3, v96, v96
	v_add_f32_e32 v2, v2, v3
	v_mul_f32_e32 v3, v87, v87
	v_fmac_f32_e32 v3, v86, v86
	v_add_f32_e32 v2, v3, v2
	v_mul_f32_e32 v3, v81, v81
	v_fmac_f32_e32 v3, v80, v80
	v_add_f32_e32 v2, v3, v2
	v_add_f32_e32 v10, v10, v2
	v_pk_mul_f32 v[2:3], v[224:225], v[96:97]
	v_pk_mul_f32 v[6:7], v[220:221], v[80:81]
	v_pk_mul_f32 v[4:5], v[226:227], v[102:103]
	v_pk_mul_f32 v[8:9], v[222:223], v[86:87]
	v_max_f32_e64 v2, |v2|, |v3|
	v_max_f32_e64 v3, |v6|, |v7|
	v_max_f32_e64 v4, |v4|, |v5|
	v_max3_f32 v3, |v8|, |v9|, v3
	v_max3_f32 v2, v4, v2, v3
	v_max3_f32 v2, v11, 0, v2
	ds_bpermute_b32 v3, v122, v10
	ds_bpermute_b32 v6, v122, v2
	v_or_b32_e32 v74, 16, v176
	v_ashrrev_i32_e32 v75, 31, v74
	s_waitcnt lgkmcnt(1)
	v_add_f32_e32 v4, v10, v3
	s_waitcnt lgkmcnt(0)
	v_max_f32_e32 v3, v6, v6
	v_max_f32_e32 v6, v2, v3
	ds_bpermute_b32 v5, v123, v4
	ds_bpermute_b32 v7, v123, v6
	v_lshlrev_b64 v[2:3], 7, v[74:75]
	s_and_saveexec_b64 s[0:1], vcc
	s_cbranch_execz .LBB0_575
	s_waitcnt lgkmcnt(0)
	v_max_f32_e32 v7, v7, v7
	v_max_f32_e32 v6, v6, v6
	v_max_f32_e32 v7, v6, v7
	v_add_f32_e32 v6, v4, v5
	v_lshl_add_u64 v[4:5], s[42:43], 0, v[2:3]
	v_lshl_add_u64 v[4:5], s[84:85], 3, v[4:5]
	s_lshl_b32 s40, s91, 3
	v_lshl_add_u64 v[4:5], v[4:5], 0, s[40:41]
	s_cmp_eq_u32 s99, 1
	s_cbranch_scc1 .Lxp_plain_2
	global_store_dwordx2 v[4:5], v[6:7], off sc1
	s_branch .Lxp_done_2
.Lxp_plain_2:
	global_store_dwordx2 v[4:5], v[6:7], off
.Lxp_done_2:
.LBB0_575:
	s_or_b64 exec, exec, s[0:1]
	v_mul_f32_e32 v4, v205, v205
	s_waitcnt lgkmcnt(1)
	v_mul_f32_e32 v5, v201, v201
	v_fmac_f32_e32 v4, v204, v204
	v_fmac_f32_e32 v5, v200, v200
	v_add_f32_e32 v4, v4, v5
	v_mul_f32_e32 v5, v199, v199
	v_fmac_f32_e32 v5, v198, v198
	v_add_f32_e32 v4, v5, v4
	v_mul_f32_e32 v5, v193, v193
	v_fmac_f32_e32 v5, v192, v192
	v_add_f32_e32 v12, v5, v4
	v_pk_mul_f32 v[4:5], v[232:233], v[200:201]
	v_pk_mul_f32 v[8:9], v[228:229], v[192:193]
	s_waitcnt lgkmcnt(0)
	v_pk_mul_f32 v[6:7], v[234:235], v[204:205]
	v_pk_mul_f32 v[10:11], v[230:231], v[198:199]
	v_max_f32_e64 v4, |v4|, |v5|
	v_max_f32_e64 v5, |v8|, |v9|
	v_max_f32_e64 v6, |v6|, |v7|
	v_max3_f32 v5, |v10|, |v11|, v5
	v_max3_f32 v13, v6, v4, v5
	v_mul_f32_e32 v4, v79, v79
	v_mul_f32_e32 v5, v71, v71
	v_fmac_f32_e32 v4, v78, v78
	v_fmac_f32_e32 v5, v70, v70
	v_add_f32_e32 v4, v4, v5
	v_mul_f32_e32 v5, v69, v69
	v_fmac_f32_e32 v5, v68, v68
	v_add_f32_e32 v4, v5, v4
	v_mul_f32_e32 v5, v65, v65
	v_fmac_f32_e32 v5, v64, v64
	v_add_f32_e32 v4, v5, v4
	v_add_f32_e32 v12, v12, v4
	v_pk_mul_f32 v[4:5], v[224:225], v[70:71]
	v_pk_mul_f32 v[8:9], v[220:221], v[64:65]
	v_pk_mul_f32 v[6:7], v[226:227], v[78:79]
	v_pk_mul_f32 v[10:11], v[222:223], v[68:69]
	v_max_f32_e64 v4, |v4|, |v5|
	v_max_f32_e64 v5, |v8|, |v9|
	v_max_f32_e64 v6, |v6|, |v7|
	v_max3_f32 v5, |v10|, |v11|, v5
	v_max3_f32 v4, v6, v4, v5
	v_max3_f32 v4, v13, 0, v4
	ds_bpermute_b32 v5, v122, v12
	ds_bpermute_b32 v8, v122, v4
	v_or_b32_e32 v76, 32, v176
	v_ashrrev_i32_e32 v77, 31, v76
	s_waitcnt lgkmcnt(1)
	v_add_f32_e32 v6, v12, v5
	s_waitcnt lgkmcnt(0)
	v_max_f32_e32 v5, v8, v8
	v_max_f32_e32 v8, v4, v5
	ds_bpermute_b32 v7, v123, v6
	ds_bpermute_b32 v9, v123, v8
	v_lshlrev_b64 v[4:5], 7, v[76:77]
	s_and_saveexec_b64 s[0:1], vcc
	s_cbranch_execz .LBB0_577
	s_waitcnt lgkmcnt(0)
	v_max_f32_e32 v9, v9, v9
	v_max_f32_e32 v8, v8, v8
	v_max_f32_e32 v9, v8, v9
	v_add_f32_e32 v8, v6, v7
	v_lshl_add_u64 v[6:7], s[42:43], 0, v[4:5]
	v_lshl_add_u64 v[6:7], s[84:85], 3, v[6:7]
	s_lshl_b32 s40, s91, 3
	v_lshl_add_u64 v[6:7], v[6:7], 0, s[40:41]
	s_cmp_eq_u32 s99, 1
	s_cbranch_scc1 .Lxp_plain_3
	global_store_dwordx2 v[6:7], v[8:9], off sc1
	s_branch .Lxp_done_3
.Lxp_plain_3:
	global_store_dwordx2 v[6:7], v[8:9], off
.Lxp_done_3:
.LBB0_577:
	s_or_b64 exec, exec, s[0:1]
	v_mul_f32_e32 v6, v195, v195
	s_waitcnt lgkmcnt(1)
	v_mul_f32_e32 v7, v191, v191
	v_fmac_f32_e32 v6, v194, v194
	v_fmac_f32_e32 v7, v190, v190
	v_add_f32_e32 v6, v6, v7
	v_mul_f32_e32 v7, v189, v189
	v_fmac_f32_e32 v7, v188, v188
	v_add_f32_e32 v6, v7, v6
	v_mul_f32_e32 v7, v187, v187
	v_fmac_f32_e32 v7, v186, v186
	v_add_f32_e32 v14, v7, v6
	v_pk_mul_f32 v[6:7], v[232:233], v[190:191]
	v_pk_mul_f32 v[10:11], v[228:229], v[186:187]
	s_waitcnt lgkmcnt(0)
	v_pk_mul_f32 v[8:9], v[234:235], v[194:195]
	v_pk_mul_f32 v[12:13], v[230:231], v[188:189]
	v_max_f32_e64 v6, |v6|, |v7|
	v_max_f32_e64 v7, |v10|, |v11|
	v_max_f32_e64 v8, |v8|, |v9|
	v_max3_f32 v7, |v12|, |v13|, v7
	v_max3_f32 v15, v8, v6, v7
	v_mul_f32_e32 v6, v67, v67
	v_mul_f32_e32 v7, v63, v63
	v_fmac_f32_e32 v6, v66, v66
	v_fmac_f32_e32 v7, v62, v62
	v_add_f32_e32 v6, v6, v7
	v_mul_f32_e32 v7, v61, v61
	v_fmac_f32_e32 v7, v60, v60
	v_add_f32_e32 v6, v7, v6
	v_mul_f32_e32 v7, v59, v59
	v_fmac_f32_e32 v7, v58, v58
	v_add_f32_e32 v6, v7, v6
	v_add_f32_e32 v14, v14, v6
	v_pk_mul_f32 v[6:7], v[224:225], v[62:63]
	v_pk_mul_f32 v[10:11], v[220:221], v[58:59]
	v_pk_mul_f32 v[8:9], v[226:227], v[66:67]
	v_pk_mul_f32 v[12:13], v[222:223], v[60:61]
	v_max_f32_e64 v6, |v6|, |v7|
	v_max_f32_e64 v7, |v10|, |v11|
	v_max_f32_e64 v8, |v8|, |v9|
	v_max3_f32 v7, |v12|, |v13|, v7
	v_max3_f32 v6, v8, v6, v7
	v_max3_f32 v6, v15, 0, v6
	ds_bpermute_b32 v7, v122, v14
	ds_bpermute_b32 v10, v122, v6
	v_or_b32_e32 v82, 48, v176
	v_ashrrev_i32_e32 v83, 31, v82
	s_waitcnt lgkmcnt(1)
	v_add_f32_e32 v8, v14, v7
	s_waitcnt lgkmcnt(0)
	v_max_f32_e32 v7, v10, v10
	v_max_f32_e32 v10, v6, v7
	ds_bpermute_b32 v9, v123, v8
	ds_bpermute_b32 v11, v123, v10
	v_lshlrev_b64 v[6:7], 7, v[82:83]
	s_and_saveexec_b64 s[0:1], vcc
	s_cbranch_execz .LBB0_579
	s_waitcnt lgkmcnt(0)
	v_max_f32_e32 v11, v11, v11
	v_max_f32_e32 v10, v10, v10
	v_max_f32_e32 v11, v10, v11
	v_add_f32_e32 v10, v8, v9
	v_lshl_add_u64 v[8:9], s[42:43], 0, v[6:7]
	v_lshl_add_u64 v[8:9], s[84:85], 3, v[8:9]
	s_lshl_b32 s40, s91, 3
	v_lshl_add_u64 v[8:9], v[8:9], 0, s[40:41]
	s_cmp_eq_u32 s99, 1
	s_cbranch_scc1 .Lxp_plain_4
	global_store_dwordx2 v[8:9], v[10:11], off sc1
	s_branch .Lxp_done_4
.Lxp_plain_4:
	global_store_dwordx2 v[8:9], v[10:11], off
.Lxp_done_4:
.LBB0_579:
	s_or_b64 exec, exec, s[0:1]
	v_mul_f32_e32 v8, v185, v185
	s_waitcnt lgkmcnt(1)
	v_mul_f32_e32 v9, v183, v183
	v_fmac_f32_e32 v8, v184, v184
	v_fmac_f32_e32 v9, v182, v182
	v_add_f32_e32 v8, v8, v9
	v_mul_f32_e32 v9, v181, v181
	v_fmac_f32_e32 v9, v180, v180
	v_add_f32_e32 v8, v9, v8
	v_mul_f32_e32 v9, v165, v165
	v_fmac_f32_e32 v9, v164, v164
	v_add_f32_e32 v16, v9, v8
	v_pk_mul_f32 v[8:9], v[232:233], v[182:183]
	v_pk_mul_f32 v[12:13], v[228:229], v[164:165]
	s_waitcnt lgkmcnt(0)
	v_pk_mul_f32 v[10:11], v[234:235], v[184:185]
	v_pk_mul_f32 v[14:15], v[230:231], v[180:181]
	v_max_f32_e64 v8, |v8|, |v9|
	v_max_f32_e64 v9, |v12|, |v13|
	v_max_f32_e64 v10, |v10|, |v11|
	v_max3_f32 v9, |v14|, |v15|, v9
	v_max3_f32 v17, v10, v8, v9
	v_mul_f32_e32 v8, v57, v57
	v_mul_f32_e32 v9, v55, v55
	v_fmac_f32_e32 v8, v56, v56
	v_fmac_f32_e32 v9, v54, v54
	v_add_f32_e32 v8, v8, v9
	v_mul_f32_e32 v9, v53, v53
	v_fmac_f32_e32 v9, v52, v52
	v_add_f32_e32 v8, v9, v8
	v_mul_f32_e32 v9, v49, v49
	v_fmac_f32_e32 v9, v48, v48
	v_add_f32_e32 v8, v9, v8
	v_add_f32_e32 v16, v16, v8
	v_pk_mul_f32 v[8:9], v[224:225], v[54:55]
	v_pk_mul_f32 v[12:13], v[220:221], v[48:49]
	v_pk_mul_f32 v[10:11], v[226:227], v[56:57]
	v_pk_mul_f32 v[14:15], v[222:223], v[52:53]
	v_max_f32_e64 v8, |v8|, |v9|
	v_max_f32_e64 v9, |v12|, |v13|
	v_max_f32_e64 v10, |v10|, |v11|
	v_max3_f32 v9, |v14|, |v15|, v9
	v_max3_f32 v8, v10, v8, v9
	v_max3_f32 v10, v17, 0, v8
	ds_bpermute_b32 v11, v122, v10
	ds_bpermute_b32 v9, v122, v16
	v_add_u32_e32 v84, 0x80, v176
	v_ashrrev_i32_e32 v85, 31, v84
	v_lshlrev_b64 v[92:93], 7, v[84:85]
	s_waitcnt lgkmcnt(1)
	v_max_f32_e32 v11, v11, v11
	s_waitcnt lgkmcnt(0)
	v_add_f32_e32 v8, v16, v9
	v_max_f32_e32 v10, v10, v11
	ds_bpermute_b32 v9, v123, v8
	ds_bpermute_b32 v11, v123, v10
	s_and_saveexec_b64 s[0:1], vcc
	s_cbranch_execz .LBB0_581
	s_waitcnt lgkmcnt(0)
	v_max_f32_e32 v11, v11, v11
	v_max_f32_e32 v10, v10, v10
	v_max_f32_e32 v11, v10, v11
	v_add_f32_e32 v10, v8, v9
	v_lshl_add_u64 v[8:9], s[42:43], 0, v[92:93]
	v_lshl_add_u64 v[8:9], s[84:85], 3, v[8:9]
	s_lshl_b32 s40, s91, 3
	v_lshl_add_u64 v[8:9], v[8:9], 0, s[40:41]
	s_cmp_eq_u32 s99, 1
	s_cbranch_scc1 .Lxp_plain_5
	global_store_dwordx2 v[8:9], v[10:11], off sc1
	s_branch .Lxp_done_5

.Lxp_done_5:
.LBB0_581:
	s_or_b64 exec, exec, s[0:1]
	v_mul_f32_e32 v8, v179, v179
	s_waitcnt lgkmcnt(1)
	v_mul_f32_e32 v9, v163, v163
	v_fmac_f32_e32 v8, v178, v178
	v_fmac_f32_e32 v9, v162, v162
	v_add_f32_e32 v8, v8, v9
	v_mul_f32_e32 v9, v161, v161
	v_fmac_f32_e32 v9, v160, v160
	v_add_f32_e32 v8, v9, v8
	v_mul_f32_e32 v9, v159, v159
	v_fmac_f32_e32 v9, v158, v158
	v_add_f32_e32 v16, v9, v8
	v_pk_mul_f32 v[8:9], v[232:233], v[162:163]
	v_pk_mul_f32 v[12:13], v[228:229], v[158:159]
	s_waitcnt lgkmcnt(0)
	v_pk_mul_f32 v[10:11], v[234:235], v[178:179]
	v_pk_mul_f32 v[14:15], v[230:231], v[160:161]
	v_max_f32_e64 v8, |v8|, |v9|
	v_max_f32_e64 v9, |v12|, |v13|
	v_max_f32_e64 v10, |v10|, |v11|
	v_max3_f32 v9, |v14|, |v15|, v9
	v_max3_f32 v17, v10, v8, v9
	v_mul_f32_e32 v8, v51, v51
	v_mul_f32_e32 v9, v47, v47
	v_fmac_f32_e32 v8, v50, v50
	v_fmac_f32_e32 v9, v46, v46
	v_add_f32_e32 v8, v8, v9
	v_mul_f32_e32 v9, v45, v45
	v_fmac_f32_e32 v9, v44, v44
	v_add_f32_e32 v8, v9, v8
	v_mul_f32_e32 v9, v43, v43
	v_fmac_f32_e32 v9, v42, v42
	v_add_f32_e32 v8, v9, v8
	v_add_f32_e32 v16, v16, v8
	v_pk_mul_f32 v[8:9], v[224:225], v[46:47]
	v_pk_mul_f32 v[12:13], v[220:221], v[42:43]
	v_pk_mul_f32 v[10:11], v[226:227], v[50:51]
	v_pk_mul_f32 v[14:15], v[222:223], v[44:45]
	v_max_f32_e64 v8, |v8|, |v9|
	v_max_f32_e64 v9, |v12|, |v13|
	v_max_f32_e64 v10, |v10|, |v11|
	v_max3_f32 v9, |v14|, |v15|, v9
	v_max3_f32 v8, v10, v8, v9
	v_max3_f32 v10, v17, 0, v8
	ds_bpermute_b32 v11, v122, v10
	ds_bpermute_b32 v9, v122, v16
	v_add_u32_e32 v90, 0x90, v176
	v_ashrrev_i32_e32 v91, 31, v90
	v_lshlrev_b64 v[100:101], 7, v[90:91]
	s_waitcnt lgkmcnt(1)
	v_max_f32_e32 v11, v11, v11
	s_waitcnt lgkmcnt(0)
	v_add_f32_e32 v8, v16, v9
	v_max_f32_e32 v10, v10, v11
	ds_bpermute_b32 v9, v123, v8
	ds_bpermute_b32 v11, v123, v10
	s_and_saveexec_b64 s[0:1], vcc
	s_cbranch_execz .LBB0_583
	s_waitcnt lgkmcnt(0)
	v_max_f32_e32 v11, v11, v11
	v_max_f32_e32 v10, v10, v10
	v_max_f32_e32 v11, v10, v11
	v_add_f32_e32 v10, v8, v9
	v_lshl_add_u64 v[8:9], s[42:43], 0, v[100:101]
	v_lshl_add_u64 v[8:9], s[84:85], 3, v[8:9]
	s_lshl_b32 s40, s91, 3
	v_lshl_add_u64 v[8:9], v[8:9], 0, s[40:41]
	s_cmp_eq_u32 s99, 1
	s_cbranch_scc1 .Lxp_plain_6
	global_store_dwordx2 v[8:9], v[10:11], off sc1
	s_branch .Lxp_done_6

.Lxp_done_6:
.LBB0_583:
	s_or_b64 exec, exec, s[0:1]
	v_mul_f32_e32 v8, v157, v157
	s_waitcnt lgkmcnt(1)
	v_mul_f32_e32 v9, v155, v155
	v_fmac_f32_e32 v8, v156, v156
	v_fmac_f32_e32 v9, v154, v154
	v_add_f32_e32 v8, v8, v9
	v_mul_f32_e32 v9, v129, v129
	v_fmac_f32_e32 v9, v128, v128
	v_add_f32_e32 v8, v9, v8
	v_mul_f32_e32 v9, v121, v121
	v_fmac_f32_e32 v9, v120, v120
	v_add_f32_e32 v16, v9, v8
	v_pk_mul_f32 v[8:9], v[232:233], v[154:155]
	v_pk_mul_f32 v[12:13], v[228:229], v[120:121]
	s_waitcnt lgkmcnt(0)
	v_pk_mul_f32 v[10:11], v[234:235], v[156:157]
	v_pk_mul_f32 v[14:15], v[230:231], v[128:129]
	v_max_f32_e64 v8, |v8|, |v9|
	v_max_f32_e64 v9, |v12|, |v13|
	v_max_f32_e64 v10, |v10|, |v11|
	v_max3_f32 v9, |v14|, |v15|, v9
	v_max3_f32 v17, v10, v8, v9
	v_mul_f32_e32 v8, v41, v41
	v_mul_f32_e32 v9, v39, v39
	v_fmac_f32_e32 v8, v40, v40
	v_fmac_f32_e32 v9, v38, v38
	v_add_f32_e32 v8, v8, v9
	v_mul_f32_e32 v9, v37, v37
	v_fmac_f32_e32 v9, v36, v36
	v_add_f32_e32 v8, v9, v8
	v_mul_f32_e32 v9, v33, v33
	v_fmac_f32_e32 v9, v32, v32
	v_add_f32_e32 v8, v9, v8
	v_add_f32_e32 v16, v16, v8
	v_pk_mul_f32 v[8:9], v[224:225], v[38:39]
	v_pk_mul_f32 v[12:13], v[220:221], v[32:33]
	v_pk_mul_f32 v[10:11], v[226:227], v[40:41]
	v_pk_mul_f32 v[14:15], v[222:223], v[36:37]
	v_max_f32_e64 v8, |v8|, |v9|
	v_max_f32_e64 v9, |v12|, |v13|
	v_max_f32_e64 v10, |v10|, |v11|
	v_max3_f32 v9, |v14|, |v15|, v9
	v_max3_f32 v8, v10, v8, v9
	v_max3_f32 v10, v17, 0, v8
	ds_bpermute_b32 v11, v122, v10
	ds_bpermute_b32 v9, v122, v16
	v_add_u32_e32 v98, 0xa0, v176
	v_ashrrev_i32_e32 v99, 31, v98
	v_lshlrev_b64 v[108:109], 7, v[98:99]
	s_waitcnt lgkmcnt(1)
	v_max_f32_e32 v11, v11, v11
	s_waitcnt lgkmcnt(0)
	v_add_f32_e32 v8, v16, v9
	v_max_f32_e32 v10, v10, v11
	ds_bpermute_b32 v9, v123, v8
	ds_bpermute_b32 v11, v123, v10
	s_and_saveexec_b64 s[0:1], vcc
	s_cbranch_execz .LBB0_585
	s_waitcnt lgkmcnt(0)
	v_max_f32_e32 v11, v11, v11
	v_max_f32_e32 v10, v10, v10
	v_max_f32_e32 v11, v10, v11
	v_add_f32_e32 v10, v8, v9
	v_lshl_add_u64 v[8:9], s[42:43], 0, v[108:109]
	v_lshl_add_u64 v[8:9], s[84:85], 3, v[8:9]
	s_lshl_b32 s40, s91, 3
	v_lshl_add_u64 v[8:9], v[8:9], 0, s[40:41]
	s_cmp_eq_u32 s99, 1
	s_cbranch_scc1 .Lxp_plain_7
	global_store_dwordx2 v[8:9], v[10:11], off sc1
	s_branch .Lxp_done_7

.Lxp_done_7:
.LBB0_585:
	s_or_b64 exec, exec, s[0:1]
	v_mul_f32_e32 v8, v127, v127
	s_waitcnt lgkmcnt(1)
	v_mul_f32_e32 v9, v119, v119
	v_fmac_f32_e32 v8, v126, v126
	v_fmac_f32_e32 v9, v118, v118
	v_add_f32_e32 v8, v8, v9
	v_mul_f32_e32 v9, v113, v113
	v_fmac_f32_e32 v9, v112, v112
	v_add_f32_e32 v8, v9, v8
	v_mul_f32_e32 v9, v111, v111
	v_fmac_f32_e32 v9, v110, v110
	v_add_f32_e32 v16, v9, v8
	v_pk_mul_f32 v[8:9], v[232:233], v[118:119]
	v_pk_mul_f32 v[12:13], v[228:229], v[110:111]
	s_waitcnt lgkmcnt(0)
	v_pk_mul_f32 v[10:11], v[234:235], v[126:127]
	v_pk_mul_f32 v[14:15], v[230:231], v[112:113]
	v_max_f32_e64 v8, |v8|, |v9|
	v_max_f32_e64 v9, |v12|, |v13|
	v_max_f32_e64 v10, |v10|, |v11|
	v_max3_f32 v9, |v14|, |v15|, v9
	v_max3_f32 v17, v10, v8, v9
	v_mul_f32_e32 v8, v35, v35
	v_mul_f32_e32 v9, v31, v31
	v_fmac_f32_e32 v8, v34, v34
	v_fmac_f32_e32 v9, v30, v30
	v_add_f32_e32 v8, v8, v9
	v_mul_f32_e32 v9, v29, v29
	v_fmac_f32_e32 v9, v28, v28
	v_add_f32_e32 v8, v9, v8
	v_mul_f32_e32 v9, v27, v27
	v_fmac_f32_e32 v9, v26, v26
	v_add_f32_e32 v8, v9, v8
	v_add_f32_e32 v16, v16, v8
	v_pk_mul_f32 v[8:9], v[224:225], v[30:31]
	v_pk_mul_f32 v[12:13], v[220:221], v[26:27]
	v_pk_mul_f32 v[10:11], v[226:227], v[34:35]
	v_pk_mul_f32 v[14:15], v[222:223], v[28:29]
	v_max_f32_e64 v8, |v8|, |v9|
	v_max_f32_e64 v9, |v12|, |v13|
	v_max_f32_e64 v10, |v10|, |v11|
	v_max3_f32 v9, |v14|, |v15|, v9
	v_max3_f32 v8, v10, v8, v9
	v_max3_f32 v10, v17, 0, v8
	ds_bpermute_b32 v11, v122, v10
	ds_bpermute_b32 v9, v122, v16
	v_add_u32_e32 v106, 0xb0, v176
	v_ashrrev_i32_e32 v107, 31, v106
	v_lshlrev_b64 v[114:115], 7, v[106:107]
	s_waitcnt lgkmcnt(1)
	v_max_f32_e32 v11, v11, v11
	s_waitcnt lgkmcnt(0)
	v_add_f32_e32 v8, v16, v9
	v_max_f32_e32 v10, v10, v11
	ds_bpermute_b32 v9, v123, v8
	ds_bpermute_b32 v11, v123, v10
	s_and_saveexec_b64 s[0:1], vcc
	s_cbranch_execz .LBB0_587
	s_waitcnt lgkmcnt(0)
	v_max_f32_e32 v11, v11, v11
	v_max_f32_e32 v10, v10, v10
	v_max_f32_e32 v11, v10, v11
	v_add_f32_e32 v10, v8, v9
	v_lshl_add_u64 v[8:9], s[42:43], 0, v[114:115]
	v_lshl_add_u64 v[8:9], s[84:85], 3, v[8:9]
	s_lshl_b32 s40, s91, 3
	v_lshl_add_u64 v[8:9], v[8:9], 0, s[40:41]
	s_cmp_eq_u32 s99, 1
	s_cbranch_scc1 .Lxp_plain_8
	global_store_dwordx2 v[8:9], v[10:11], off sc1
	s_branch .Lxp_done_8

.Lxp_done_8:
.LBB0_587:
	s_or_b64 exec, exec, s[0:1]
	s_lshl_b32 s0, s46, 6
	s_ashr_i32 s1, s0, 31
	s_waitcnt vmcnt(0)
	s_lshl_b64 s[0:1], s[0:1], 2
	v_readlane_b32 s34, v255, 6
	s_add_u32 s0, s34, s0
	s_addc_u32 s1, s86, s1
	s_and_saveexec_b64 s[34:35], s[2:3]
	s_cbranch_execz .LBB0_590
	s_cmp_eq_u32 s99, 1
	s_cbranch_scc0 .Lxs7_at
	s_lshr_b32 s40, s27, 6
	s_lshl_b32 s40, s40, 3
	s_add_i32 s40, s40, s32
	s_lshl_b32 s40, s40, 2
	s_lshl_b32 s98, s46, 7
	s_sub_i32 s98, 0x60000, s98
	s_add_i32 s40, s40, s98
	v_mov_b32_e32 v8, s40
	v_mov_b32_e32 v9, 1
	global_store_dword v8, v9, s[0:1]
	s_branch .LBB0_590
.Lxs7_at:
	s_mov_b64 s[66:67], exec
	v_mbcnt_lo_u32_b32 v8, s66, 0
	v_mbcnt_hi_u32_b32 v8, s67, v8
	v_cmp_eq_u32_e32 vcc, 0, v8
	s_and_b64 s[74:75], exec, vcc
	s_mov_b64 exec, s[74:75]
	s_cbranch_execz .LBB0_590
	s_bcnt1_i32_b64 s40, s[66:67]
	v_mov_b32_e32 v8, s40
	global_atomic_add v169, v8, s[0:1]
.LBB0_590:
	s_or_b64 exec, exec, s[34:35]
	s_mov_b64 s[34:35], exec
	v_readlane_b32 s66, v254, 10
	v_readlane_b32 s67, v254, 11
	s_and_b64 s[66:67], s[34:35], s[66:67]
	s_mov_b64 exec, s[66:67]
	s_cbranch_execz .LBB0_596
	s_cmp_eq_u32 s99, 1
	s_cbranch_scc0 .Lxs7_po
	v_and_b32_e32 v8, 31, v0
	v_lshlrev_b32_e32 v8, 2, v8
	v_add_u32_e32 v8, s98, v8
	s_mov_b32 s40, 0x100001
.Lxs7_spin:
	global_load_dword v9, v8, s[0:1] sc1
	s_waitcnt vmcnt(0)
	v_cmp_gt_u32_e32 vcc, 1, v9
	s_cbranch_vccz .LBB0_595
	s_add_i32 s40, s40, -1
	s_cmp_eq_u32 s40, 0
	s_cbranch_scc1 .LBB0_595
	s_sleep 1
	s_branch .Lxs7_spin
.Lxs7_po:
	s_mov_b32 s40, 0x100001
	s_branch .LBB0_593

.LBB0_701:
	v_mov_b32_e32 v1, s88
	ds_read_b32 v1, v1 offset:8
	v_readfirstlane_b32 s32, v0
	s_waitcnt lgkmcnt(0)
	v_readfirstlane_b32 s99, v1
	s_lshr_b32 s32, s32, 6
	v_mov_b32_e32 v1, s88
	ds_read_b32 v1, v1 offset:8
	s_waitcnt lgkmcnt(0)
	v_readfirstlane_b32 s99, v1
	s_cmp_lt_i32 s30, 10
	s_cselect_b64 s[0:1], -1, 0
	s_and_b64 s[0:1], s[0:1], s[2:3]
	s_andn2_b64 vcc, exec, s[0:1]
	s_cbranch_vccnz .LBB0_753
	s_cmpk_lt_i32 s24, 0x200
	s_cselect_b64 s[0:1], -1, 0
	s_cmpk_gt_i32 s24, 0x1ff
	v_readfirstlane_b32 s4, v0
	s_cbranch_scc1 .LBB0_704
	s_ashr_i32 s2, s24, 31
	s_lshr_b32 s2, s2, 29
	s_add_i32 s2, s24, s2
	s_ashr_i32 s3, s2, 3
	s_and_b32 s2, s2, -8
	s_sub_i32 s2, s24, s2
	s_lshl_b32 s6, s2, 6
	s_mul_i32 s5, s2, 0x41
	s_cmp_lt_i32 s2, 0
	s_cselect_b32 s2, s5, s6
	s_add_i32 s2, s2, s3
	s_ashr_i32 s3, s2, 31
	s_lshr_b32 s3, s3, 27
	s_add_i32 s3, s2, s3
	s_ashr_i32 s5, s3, 5
	s_and_b32 s3, s3, 0xffe0
	s_sub_i32 s2, s2, s3
	s_bfe_i32 s3, s2, 0x80000
	s_bfe_u32 s3, s3, 0x3000c
	s_add_i32 s3, s2, s3
	s_bfe_i32 s6, s3, 0x80000
	s_and_b32 s3, s3, 0xf8
	s_sub_i32 s2, s2, s3
	s_lshl_b32 s5, s5, 3
	s_sext_i32_i16 s6, s6
	s_sext_i32_i8 s2, s2
	s_add_i32 s34, s5, s2
	s_ashr_i32 s14, s6, 3

.LBB0_724:
	v_mbcnt_lo_u32_b32 v196, -1, 0
	v_mbcnt_hi_u32_b32 v196, -1, v196
	s_lshl_b32 s64, s14, 8
	v_ashrrev_i32_e32 v225, 4, v196
	v_lshlrev_b32_e32 v223, 3, v225
	s_or_b32 s0, s64, s83
	s_ashr_i32 s66, s34, 4
	v_add_u32_e32 v128, s0, v223
	s_lshl_b32 s0, s14, 2
	s_mul_hi_i32 s67, s66, 0xb000
	s_mul_i32 s66, s66, 0xb000
	s_ashr_i32 s1, s0, 31
	s_add_u32 s6, s69, s66
	v_ashrrev_i32_e32 v129, 31, v128
	s_addc_u32 s7, s70, s67
	v_lshl_add_u64 v[130:131], v[128:129], 2, s[6:7]
	v_and_or_b32 v129, v196, 15, s82
	v_lshl_add_u32 v198, s34, 8, v129
	v_lshlrev_b32_e32 v128, 2, v128
	v_lshl_add_u32 v240, v198, 12, v128
	v_lshrrev_b32_e32 v128, 1, v240
	global_load_dwordx4 v[192:195], v[130:131], off offset:16
	global_load_dwordx4 v[200:203], v[130:131], off
	global_load_dwordx4 v[64:67], v[130:131], off offset:528
	global_load_dwordx4 v[204:207], v[130:131], off offset:512
	global_load_dwordx4 v[68:71], v128, s[38:39]
	v_add_u32_e32 v135, 0x200, v240
	v_lshrrev_b32_e32 v135, 1, v135
	global_load_dwordx4 v[234:237], v135, s[38:39]
	v_add_u32_e32 v128, 0x10000, v240
	v_add_u32_e32 v129, 0x20000, v240
	v_add_u32_e32 v130, 0x30000, v240
	v_add_u32_e32 v131, 0x80000, v240
	v_add_u32_e32 v132, 0x90000, v240
	v_add_u32_e32 v133, 0xa0000, v240
	v_add_u32_e32 v134, 0xb0000, v240
	v_add_u32_e32 v135, 0x10200, v240
	v_add_u32_e32 v136, 0x20200, v240
	v_add_u32_e32 v137, 0x30200, v240
	v_add_u32_e32 v138, 0x80200, v240
	v_add_u32_e32 v139, 0x90200, v240
	v_add_u32_e32 v140, 0xa0200, v240
	v_add_u32_e32 v141, 0xb0200, v240
	v_lshrrev_b32_e32 v128, 1, v128
	v_lshrrev_b32_e32 v129, 1, v129
	v_lshrrev_b32_e32 v130, 1, v130
	v_lshrrev_b32_e32 v131, 1, v131
	v_lshrrev_b32_e32 v132, 1, v132
	v_lshrrev_b32_e32 v133, 1, v133
	v_lshrrev_b32_e32 v134, 1, v134
	v_lshrrev_b32_e32 v135, 1, v135
	v_lshrrev_b32_e32 v142, 1, v136
	v_lshrrev_b32_e32 v143, 1, v137
	v_lshrrev_b32_e32 v148, 1, v138
	v_lshrrev_b32_e32 v149, 1, v139
	v_lshrrev_b32_e32 v140, 1, v140
	v_lshrrev_b32_e32 v184, 1, v141
	global_load_dwordx4 v[176:179], v128, s[38:39]
	global_load_dwordx4 v[168:171], v129, s[38:39]
	global_load_dwordx4 v[160:163], v130, s[38:39]
	global_load_dwordx4 v[152:155], v131, s[38:39]
	global_load_dwordx4 v[144:147], v132, s[38:39]
	global_load_dwordx4 v[136:139], v133, s[38:39]
	s_nop 0
	global_load_dwordx4 v[128:131], v134, s[38:39]
	global_load_dwordx4 v[180:183], v135, s[38:39]
	global_load_dwordx4 v[172:175], v142, s[38:39]
	global_load_dwordx4 v[164:167], v143, s[38:39]
	global_load_dwordx4 v[156:159], v148, s[38:39]
	s_nop 0
	global_load_dwordx4 v[148:151], v149, s[38:39]
	s_nop 0
	global_load_dwordx4 v[140:143], v140, s[38:39]
	s_nop 0
	global_load_dwordx4 v[132:135], v184, s[38:39]
	v_and_b32_e32 v185, 64, v221
	v_xor_b32_e32 v184, 16, v221
	v_add_u32_e32 v197, 64, v185
	v_cmp_lt_i32_e32 vcc, v184, v197
	s_waitcnt vmcnt(0)
	v_pk_mul_f32 v[208:209], v[192:193], s[46:47] op_sel_hi:[1,0]
	v_cndmask_b32_e32 v184, v221, v184, vcc
	v_lshlrev_b32_e32 v222, 2, v184
	v_pk_mul_f32 v[214:215], v[202:203], s[46:47] op_sel_hi:[1,0]
	v_pk_mul_f32 v[212:213], v[200:201], s[46:47] op_sel_hi:[1,0]
	v_lshlrev_b32_e32 v184, 16, v68
	v_and_b32_e32 v185, 0xffff0000, v68
	v_lshlrev_b32_e32 v186, 16, v69
	v_and_b32_e32 v187, 0xffff0000, v69
	v_pk_fma_f32 v[126:127], v[126:127], v[214:215], v[186:187]
	v_pk_fma_f32 v[124:125], v[124:125], v[212:213], v[184:185]
	v_lshlrev_b32_e32 v192, 16, v70
	v_and_b32_e32 v193, 0xffff0000, v70
	v_mul_f32_e32 v184, v125, v125
	v_mul_f32_e32 v185, v127, v127
	v_pk_fma_f32 v[120:121], v[120:121], v[208:209], v[192:193]
	v_fmac_f32_e32 v184, v124, v124
	v_fmac_f32_e32 v185, v126, v126
	v_pk_mul_f32 v[210:211], v[194:195], s[46:47] op_sel_hi:[1,0]
	v_lshlrev_b32_e32 v194, 16, v71
	v_and_b32_e32 v195, 0xffff0000, v71
	v_add_f32_e32 v184, v184, v185
	v_mul_f32_e32 v185, v121, v121
	v_pk_fma_f32 v[122:123], v[122:123], v[210:211], v[194:195]
	v_fmac_f32_e32 v185, v120, v120
	v_add_f32_e32 v184, v185, v184
	v_mul_f32_e32 v185, v123, v123
	v_fmac_f32_e32 v185, v122, v122
	v_pk_mul_f32 v[206:207], v[206:207], s[46:47] op_sel_hi:[1,0]
	v_pk_mul_f32 v[204:205], v[204:205], s[46:47] op_sel_hi:[1,0]
	v_add_f32_e32 v199, v185, v184
	v_lshlrev_b32_e32 v184, 16, v234
	v_and_b32_e32 v185, 0xffff0000, v234
	v_lshlrev_b32_e32 v186, 16, v235
	v_and_b32_e32 v187, 0xffff0000, v235
	v_pk_fma_f32 v[118:119], v[118:119], v[206:207], v[186:187]
	v_pk_fma_f32 v[116:117], v[116:117], v[204:205], v[184:185]
	v_pk_mul_f32 v[200:201], v[64:65], s[46:47] op_sel_hi:[1,0]
	v_lshlrev_b32_e32 v192, 16, v236
	v_and_b32_e32 v193, 0xffff0000, v236
	v_mul_f32_e32 v184, v117, v117
	v_mul_f32_e32 v185, v119, v119
	v_pk_fma_f32 v[112:113], v[112:113], v[200:201], v[192:193]
	v_fmac_f32_e32 v184, v116, v116
	v_fmac_f32_e32 v185, v118, v118
	v_pk_mul_f32 v[202:203], v[66:67], s[46:47] op_sel_hi:[1,0]
	v_lshlrev_b32_e32 v194, 16, v237
	v_and_b32_e32 v195, 0xffff0000, v237
	v_add_f32_e32 v184, v184, v185
	v_mul_f32_e32 v185, v113, v113
	v_pk_fma_f32 v[114:115], v[114:115], v[202:203], v[194:195]
	v_fmac_f32_e32 v185, v112, v112
	v_add_f32_e32 v184, v185, v184
	v_mul_f32_e32 v185, v115, v115
	v_fmac_f32_e32 v185, v114, v114
	v_add_f32_e32 v184, v185, v184
	v_add_f32_e32 v184, v199, v184
	ds_bpermute_b32 v185, v222, v184
	v_xor_b32_e32 v186, 32, v221
	v_cmp_lt_i32_e32 vcc, v186, v197
	v_ashrrev_i32_e32 v199, 31, v198
	s_waitcnt lgkmcnt(0)
	v_add_f32_e32 v8, v184, v185
	v_cndmask_b32_e32 v186, v221, v186, vcc
	v_lshlrev_b32_e32 v224, 2, v186
	ds_bpermute_b32 v9, v224, v8
	v_cmp_gt_u32_e32 vcc, 16, v196
	v_lshlrev_b64 v[196:197], 6, v[198:199]
	s_and_saveexec_b64 s[6:7], vcc
	s_cbranch_execz .LBB0_726
	v_lshl_add_u64 v[184:185], s[30:31], 0, v[196:197]
	v_lshl_add_u64 v[184:185], s[0:1], 2, v[184:185]
	s_lshl_b32 s14, s81, 2
	s_waitcnt lgkmcnt(0)
	v_add_f32_e32 v186, v8, v9
	v_lshl_add_u64 v[184:185], v[184:185], 0, s[14:15]
	s_cmp_eq_u32 s99, 1
	s_cbranch_scc1 .Lxp_plain_9
	global_store_dword v[184:185], v186, off sc1
	s_branch .Lxp_done_9
.Lxp_plain_9:
	global_store_dword v[184:185], v186, off
.Lxp_done_9:
.LBB0_726:
	s_or_b64 exec, exec, s[6:7]
	v_lshlrev_b32_e32 v184, 16, v176
	v_and_b32_e32 v185, 0xffff0000, v176
	v_lshlrev_b32_e32 v176, 16, v177
	v_and_b32_e32 v177, 0xffff0000, v177
	v_pk_fma_f32 v[110:111], v[110:111], v[214:215], v[176:177]
	v_pk_fma_f32 v[108:109], v[108:109], v[212:213], v[184:185]
	v_lshlrev_b32_e32 v186, 16, v178
	v_and_b32_e32 v187, 0xffff0000, v178
	v_mul_f32_e32 v176, v109, v109
	v_mul_f32_e32 v177, v111, v111
	v_pk_fma_f32 v[104:105], v[104:105], v[208:209], v[186:187]
	v_fmac_f32_e32 v176, v108, v108
	v_fmac_f32_e32 v177, v110, v110
	v_lshlrev_b32_e32 v178, 16, v179
	v_and_b32_e32 v179, 0xffff0000, v179
	v_add_f32_e32 v176, v176, v177
	v_mul_f32_e32 v177, v105, v105
	v_pk_fma_f32 v[106:107], v[106:107], v[210:211], v[178:179]
	v_fmac_f32_e32 v177, v104, v104
	v_add_f32_e32 v176, v177, v176
	v_mul_f32_e32 v177, v107, v107
	v_fmac_f32_e32 v177, v106, v106
	v_add_f32_e32 v184, v177, v176
	v_lshlrev_b32_e32 v176, 16, v180
	v_and_b32_e32 v177, 0xffff0000, v180
	v_lshlrev_b32_e32 v178, 16, v181
	v_and_b32_e32 v179, 0xffff0000, v181
	v_pk_fma_f32 v[102:103], v[102:103], v[206:207], v[178:179]
	v_pk_fma_f32 v[100:101], v[100:101], v[204:205], v[176:177]
	v_lshlrev_b32_e32 v180, 16, v182
	v_and_b32_e32 v181, 0xffff0000, v182
	v_mul_f32_e32 v176, v101, v101
	v_mul_f32_e32 v177, v103, v103
	v_pk_fma_f32 v[96:97], v[96:97], v[200:201], v[180:181]
	v_fmac_f32_e32 v176, v100, v100
	v_fmac_f32_e32 v177, v102, v102
	v_lshlrev_b32_e32 v182, 16, v183
	v_and_b32_e32 v183, 0xffff0000, v183
	v_add_f32_e32 v176, v176, v177
	v_mul_f32_e32 v177, v97, v97
	v_pk_fma_f32 v[98:99], v[98:99], v[202:203], v[182:183]
	v_fmac_f32_e32 v177, v96, v96
	v_add_f32_e32 v176, v177, v176
	v_mul_f32_e32 v177, v99, v99
	v_fmac_f32_e32 v177, v98, v98
	v_add_f32_e32 v176, v177, v176
	v_add_f32_e32 v176, v184, v176
	ds_bpermute_b32 v177, v222, v176
	s_waitcnt lgkmcnt(0)
	v_add_f32_e32 v178, v176, v177
	ds_bpermute_b32 v179, v224, v178
	v_or_b32_e32 v176, 16, v198
	v_ashrrev_i32_e32 v177, 31, v176
	v_lshlrev_b64 v[176:177], 6, v[176:177]
	s_and_saveexec_b64 s[6:7], vcc
	s_cbranch_execz .LBB0_728
	s_waitcnt lgkmcnt(0)
	v_add_f32_e32 v180, v178, v179
	v_lshl_add_u64 v[178:179], s[30:31], 0, v[176:177]
	v_lshl_add_u64 v[178:179], s[0:1], 2, v[178:179]
	s_lshl_b32 s14, s81, 2
	v_lshl_add_u64 v[178:179], v[178:179], 0, s[14:15]
	s_cmp_eq_u32 s99, 1
	s_cbranch_scc1 .Lxp_plain_10
	global_store_dword v[178:179], v180, off sc1
	s_branch .Lxp_done_10
.Lxp_plain_10:
	global_store_dword v[178:179], v180, off
.Lxp_done_10:
.LBB0_728:
	s_or_b64 exec, exec, s[6:7]
	v_lshlrev_b32_e32 v178, 16, v168
	s_waitcnt lgkmcnt(0)
	v_and_b32_e32 v179, 0xffff0000, v168
	v_lshlrev_b32_e32 v168, 16, v169
	v_and_b32_e32 v169, 0xffff0000, v169
	v_pk_fma_f32 v[94:95], v[94:95], v[214:215], v[168:169]
	v_pk_fma_f32 v[92:93], v[92:93], v[212:213], v[178:179]
	v_lshlrev_b32_e32 v180, 16, v170
	v_and_b32_e32 v181, 0xffff0000, v170
	v_mul_f32_e32 v168, v93, v93
	v_mul_f32_e32 v169, v95, v95
	v_pk_fma_f32 v[88:89], v[88:89], v[208:209], v[180:181]
	v_fmac_f32_e32 v168, v92, v92
	v_fmac_f32_e32 v169, v94, v94
	v_lshlrev_b32_e32 v170, 16, v171
	v_and_b32_e32 v171, 0xffff0000, v171
	v_add_f32_e32 v168, v168, v169
	v_mul_f32_e32 v169, v89, v89
	v_pk_fma_f32 v[90:91], v[90:91], v[210:211], v[170:171]
	v_fmac_f32_e32 v169, v88, v88
	v_add_f32_e32 v168, v169, v168
	v_mul_f32_e32 v169, v91, v91
	v_fmac_f32_e32 v169, v90, v90
	v_add_f32_e32 v178, v169, v168
	v_lshlrev_b32_e32 v168, 16, v172
	v_and_b32_e32 v169, 0xffff0000, v172
	v_lshlrev_b32_e32 v170, 16, v173
	v_and_b32_e32 v171, 0xffff0000, v173
	v_pk_fma_f32 v[86:87], v[86:87], v[206:207], v[170:171]
	v_pk_fma_f32 v[84:85], v[84:85], v[204:205], v[168:169]
	v_lshlrev_b32_e32 v172, 16, v174
	v_and_b32_e32 v173, 0xffff0000, v174
	v_mul_f32_e32 v168, v85, v85
	v_mul_f32_e32 v169, v87, v87
	v_pk_fma_f32 v[80:81], v[80:81], v[200:201], v[172:173]
	v_fmac_f32_e32 v168, v84, v84
	v_fmac_f32_e32 v169, v86, v86
	v_lshlrev_b32_e32 v174, 16, v175
	v_and_b32_e32 v175, 0xffff0000, v175
	v_add_f32_e32 v168, v168, v169
	v_mul_f32_e32 v169, v81, v81
	v_pk_fma_f32 v[82:83], v[82:83], v[202:203], v[174:175]
	v_fmac_f32_e32 v169, v80, v80
	v_add_f32_e32 v168, v169, v168
	v_mul_f32_e32 v169, v83, v83
	v_fmac_f32_e32 v169, v82, v82
	v_add_f32_e32 v168, v169, v168
	v_add_f32_e32 v168, v178, v168
	ds_bpermute_b32 v169, v222, v168
	s_waitcnt lgkmcnt(0)
	v_add_f32_e32 v170, v168, v169
	ds_bpermute_b32 v171, v224, v170
	v_or_b32_e32 v168, 32, v198
	v_ashrrev_i32_e32 v169, 31, v168
	v_lshlrev_b64 v[168:169], 6, v[168:169]
	s_and_saveexec_b64 s[6:7], vcc
	s_cbranch_execz .LBB0_730
	s_waitcnt lgkmcnt(0)
	v_add_f32_e32 v172, v170, v171
	v_lshl_add_u64 v[170:171], s[30:31], 0, v[168:169]
	v_lshl_add_u64 v[170:171], s[0:1], 2, v[170:171]
	s_lshl_b32 s14, s81, 2
	v_lshl_add_u64 v[170:171], v[170:171], 0, s[14:15]
	s_cmp_eq_u32 s99, 1
	s_cbranch_scc1 .Lxp_plain_11
	global_store_dword v[170:171], v172, off sc1
	s_branch .Lxp_done_11
.Lxp_plain_11:
	global_store_dword v[170:171], v172, off
.Lxp_done_11:
.LBB0_730:
	s_or_b64 exec, exec, s[6:7]
	v_lshlrev_b32_e32 v170, 16, v160
	s_waitcnt lgkmcnt(0)
	v_and_b32_e32 v171, 0xffff0000, v160
	v_lshlrev_b32_e32 v160, 16, v161
	v_and_b32_e32 v161, 0xffff0000, v161
	v_pk_fma_f32 v[78:79], v[78:79], v[214:215], v[160:161]
	v_pk_fma_f32 v[76:77], v[76:77], v[212:213], v[170:171]
	v_lshlrev_b32_e32 v172, 16, v162
	v_and_b32_e32 v173, 0xffff0000, v162
	v_mul_f32_e32 v160, v77, v77
	v_mul_f32_e32 v161, v79, v79
	v_pk_fma_f32 v[72:73], v[72:73], v[208:209], v[172:173]
	v_fmac_f32_e32 v160, v76, v76
	v_fmac_f32_e32 v161, v78, v78
	v_lshlrev_b32_e32 v162, 16, v163
	v_and_b32_e32 v163, 0xffff0000, v163
	v_add_f32_e32 v160, v160, v161
	v_mul_f32_e32 v161, v73, v73
	v_pk_fma_f32 v[74:75], v[74:75], v[210:211], v[162:163]
	v_fmac_f32_e32 v161, v72, v72
	v_add_f32_e32 v160, v161, v160
	v_mul_f32_e32 v161, v75, v75
	v_fmac_f32_e32 v161, v74, v74
	v_add_f32_e32 v170, v161, v160
	v_lshlrev_b32_e32 v160, 16, v164
	v_and_b32_e32 v161, 0xffff0000, v164
	v_lshlrev_b32_e32 v162, 16, v165
	v_and_b32_e32 v163, 0xffff0000, v165
	v_pk_fma_f32 v[70:71], v[26:27], v[206:207], v[162:163]
	v_pk_fma_f32 v[68:69], v[24:25], v[204:205], v[160:161]
	v_lshlrev_b32_e32 v164, 16, v166
	v_and_b32_e32 v165, 0xffff0000, v166
	v_mul_f32_e32 v160, v69, v69
	v_mul_f32_e32 v161, v71, v71
	v_pk_fma_f32 v[64:65], v[10:11], v[200:201], v[164:165]
	v_fmac_f32_e32 v160, v68, v68
	v_fmac_f32_e32 v161, v70, v70
	v_lshlrev_b32_e32 v166, 16, v167
	v_and_b32_e32 v167, 0xffff0000, v167
	v_add_f32_e32 v160, v160, v161
	v_mul_f32_e32 v161, v65, v65
	v_pk_fma_f32 v[66:67], v[12:13], v[202:203], v[166:167]
	v_fmac_f32_e32 v161, v64, v64
	v_add_f32_e32 v160, v161, v160
	v_mul_f32_e32 v161, v67, v67
	v_fmac_f32_e32 v161, v66, v66
	v_add_f32_e32 v160, v161, v160
	v_add_f32_e32 v160, v170, v160
	ds_bpermute_b32 v161, v222, v160
	s_waitcnt lgkmcnt(0)
	v_add_f32_e32 v162, v160, v161
	ds_bpermute_b32 v163, v224, v162
	v_or_b32_e32 v160, 48, v198
	v_ashrrev_i32_e32 v161, 31, v160
	v_lshlrev_b64 v[160:161], 6, v[160:161]
	s_and_saveexec_b64 s[6:7], vcc
	s_cbranch_execz .LBB0_732
	s_waitcnt lgkmcnt(0)
	v_add_f32_e32 v164, v162, v163
	v_lshl_add_u64 v[162:163], s[30:31], 0, v[160:161]
	v_lshl_add_u64 v[162:163], s[0:1], 2, v[162:163]
	s_lshl_b32 s14, s81, 2
	v_lshl_add_u64 v[162:163], v[162:163], 0, s[14:15]
	s_cmp_eq_u32 s99, 1
	s_cbranch_scc1 .Lxp_plain_12
	global_store_dword v[162:163], v164, off sc1
	s_branch .Lxp_done_12
.Lxp_plain_12:
	global_store_dword v[162:163], v164, off
.Lxp_done_12:
.LBB0_732:
	s_or_b64 exec, exec, s[6:7]
	v_lshlrev_b32_e32 v162, 16, v152
	s_waitcnt lgkmcnt(0)
	v_and_b32_e32 v163, 0xffff0000, v152
	v_lshlrev_b32_e32 v152, 16, v153
	v_and_b32_e32 v153, 0xffff0000, v153
	v_pk_fma_f32 v[62:63], v[62:63], v[214:215], v[152:153]
	v_pk_fma_f32 v[60:61], v[60:61], v[212:213], v[162:163]
	v_lshlrev_b32_e32 v164, 16, v154
	v_and_b32_e32 v165, 0xffff0000, v154
	v_mul_f32_e32 v152, v61, v61
	v_mul_f32_e32 v153, v63, v63
	v_pk_fma_f32 v[56:57], v[56:57], v[208:209], v[164:165]
	v_fmac_f32_e32 v152, v60, v60
	v_fmac_f32_e32 v153, v62, v62
	v_lshlrev_b32_e32 v154, 16, v155
	v_and_b32_e32 v155, 0xffff0000, v155
	v_add_f32_e32 v152, v152, v153
	v_mul_f32_e32 v153, v57, v57
	v_pk_fma_f32 v[58:59], v[58:59], v[210:211], v[154:155]
	v_fmac_f32_e32 v153, v56, v56
	v_add_f32_e32 v152, v153, v152
	v_mul_f32_e32 v153, v59, v59
	v_fmac_f32_e32 v153, v58, v58
	v_add_f32_e32 v162, v153, v152
	v_lshlrev_b32_e32 v152, 16, v156
	v_and_b32_e32 v153, 0xffff0000, v156
	v_lshlrev_b32_e32 v154, 16, v157
	v_and_b32_e32 v155, 0xffff0000, v157
	v_pk_fma_f32 v[54:55], v[54:55], v[206:207], v[154:155]
	v_pk_fma_f32 v[52:53], v[52:53], v[204:205], v[152:153]
	v_lshlrev_b32_e32 v156, 16, v158
	v_and_b32_e32 v157, 0xffff0000, v158
	v_mul_f32_e32 v152, v53, v53
	v_mul_f32_e32 v153, v55, v55
	v_pk_fma_f32 v[48:49], v[48:49], v[200:201], v[156:157]
	v_fmac_f32_e32 v152, v52, v52
	v_fmac_f32_e32 v153, v54, v54
	v_lshlrev_b32_e32 v158, 16, v159
	v_and_b32_e32 v159, 0xffff0000, v159
	v_add_f32_e32 v152, v152, v153
	v_mul_f32_e32 v153, v49, v49
	v_pk_fma_f32 v[50:51], v[50:51], v[202:203], v[158:159]
	v_fmac_f32_e32 v153, v48, v48
	v_add_f32_e32 v152, v153, v152
	v_mul_f32_e32 v153, v51, v51
	v_fmac_f32_e32 v153, v50, v50
	v_add_f32_e32 v152, v153, v152
	v_add_f32_e32 v152, v162, v152
	ds_bpermute_b32 v153, v222, v152
	v_lshlrev_b64 v[154:155], 6, v[198:199]
	s_waitcnt lgkmcnt(0)
	v_add_f32_e32 v156, v152, v153
	ds_bpermute_b32 v157, v224, v156
	v_lshl_add_u64 v[152:153], v[154:155], 0, s[18:19]
	s_and_saveexec_b64 s[6:7], vcc
	s_cbranch_execz .LBB0_734
	s_waitcnt lgkmcnt(0)
	v_add_f32_e32 v158, v156, v157
	v_lshl_add_u64 v[156:157], s[30:31], 0, v[152:153]
	v_lshl_add_u64 v[156:157], s[0:1], 2, v[156:157]
	s_lshl_b32 s14, s81, 2
	v_lshl_add_u64 v[156:157], v[156:157], 0, s[14:15]
	s_cmp_eq_u32 s99, 1
	s_cbranch_scc1 .Lxp_plain_13
	global_store_dword v[156:157], v158, off sc1
	s_branch .Lxp_done_13
.Lxp_plain_13:
	global_store_dword v[156:157], v158, off
.Lxp_done_13:
.LBB0_734:
	s_or_b64 exec, exec, s[6:7]
	v_lshlrev_b32_e32 v156, 16, v144
	s_waitcnt lgkmcnt(0)
	v_and_b32_e32 v157, 0xffff0000, v144
	v_lshlrev_b32_e32 v144, 16, v145
	v_and_b32_e32 v145, 0xffff0000, v145
	v_pk_fma_f32 v[46:47], v[46:47], v[214:215], v[144:145]
	v_pk_fma_f32 v[44:45], v[44:45], v[212:213], v[156:157]
	v_lshlrev_b32_e32 v158, 16, v146
	v_and_b32_e32 v159, 0xffff0000, v146
	v_mul_f32_e32 v144, v45, v45
	v_mul_f32_e32 v145, v47, v47
	v_pk_fma_f32 v[40:41], v[40:41], v[208:209], v[158:159]
	v_fmac_f32_e32 v144, v44, v44
	v_fmac_f32_e32 v145, v46, v46
	v_lshlrev_b32_e32 v146, 16, v147
	v_and_b32_e32 v147, 0xffff0000, v147
	v_add_f32_e32 v144, v144, v145
	v_mul_f32_e32 v145, v41, v41
	v_pk_fma_f32 v[42:43], v[42:43], v[210:211], v[146:147]
	v_fmac_f32_e32 v145, v40, v40
	v_add_f32_e32 v144, v145, v144
	v_mul_f32_e32 v145, v43, v43
	v_fmac_f32_e32 v145, v42, v42
	v_add_f32_e32 v156, v145, v144
	v_lshlrev_b32_e32 v144, 16, v148
	v_and_b32_e32 v145, 0xffff0000, v148
	v_lshlrev_b32_e32 v146, 16, v149
	v_and_b32_e32 v147, 0xffff0000, v149
	v_pk_fma_f32 v[38:39], v[38:39], v[206:207], v[146:147]
	v_pk_fma_f32 v[36:37], v[36:37], v[204:205], v[144:145]
	v_lshlrev_b32_e32 v148, 16, v150
	v_and_b32_e32 v149, 0xffff0000, v150
	v_mul_f32_e32 v144, v37, v37
	v_mul_f32_e32 v145, v39, v39
	v_pk_fma_f32 v[32:33], v[32:33], v[200:201], v[148:149]
	v_fmac_f32_e32 v144, v36, v36
	v_fmac_f32_e32 v145, v38, v38
	v_lshlrev_b32_e32 v150, 16, v151
	v_and_b32_e32 v151, 0xffff0000, v151
	v_add_f32_e32 v144, v144, v145
	v_mul_f32_e32 v145, v33, v33
	v_pk_fma_f32 v[34:35], v[34:35], v[202:203], v[150:151]
	v_fmac_f32_e32 v145, v32, v32
	v_add_f32_e32 v144, v145, v144
	v_mul_f32_e32 v145, v35, v35
	v_fmac_f32_e32 v145, v34, v34
	v_add_f32_e32 v144, v145, v144
	v_add_f32_e32 v144, v156, v144
	ds_bpermute_b32 v145, v222, v144
	v_lshl_add_u64 v[148:149], v[154:155], 0, s[26:27]
	s_waitcnt lgkmcnt(0)
	v_add_f32_e32 v144, v144, v145
	ds_bpermute_b32 v145, v224, v144
	s_and_saveexec_b64 s[6:7], vcc
	s_cbranch_execz .LBB0_736
	s_waitcnt lgkmcnt(0)
	v_add_f32_e32 v146, v144, v145
	v_lshl_add_u64 v[144:145], s[30:31], 0, v[148:149]
	v_lshl_add_u64 v[144:145], s[0:1], 2, v[144:145]
	s_lshl_b32 s14, s81, 2
	v_lshl_add_u64 v[144:145], v[144:145], 0, s[14:15]
	s_cmp_eq_u32 s99, 1
	s_cbranch_scc1 .Lxp_plain_14
	global_store_dword v[144:145], v146, off sc1
	s_branch .Lxp_done_14
.Lxp_plain_14:
	global_store_dword v[144:145], v146, off
.Lxp_done_14:
.LBB0_736:
	s_or_b64 exec, exec, s[6:7]
	v_lshlrev_b32_e32 v146, 16, v136
	v_and_b32_e32 v147, 0xffff0000, v136
	v_lshlrev_b32_e32 v136, 16, v137
	v_and_b32_e32 v137, 0xffff0000, v137
	s_waitcnt lgkmcnt(0)
	v_pk_fma_f32 v[144:145], v[30:31], v[214:215], v[136:137]
	v_pk_fma_f32 v[146:147], v[28:29], v[212:213], v[146:147]
	v_lshlrev_b32_e32 v150, 16, v138
	v_and_b32_e32 v151, 0xffff0000, v138
	v_lshlrev_b32_e32 v138, 16, v139
	v_and_b32_e32 v139, 0xffff0000, v139
	v_mul_f32_e32 v24, v147, v147
	v_mul_f32_e32 v25, v145, v145
	v_pk_fma_f32 v[136:137], v[244:245], v[210:211], v[138:139]
	v_pk_fma_f32 v[138:139], v[242:243], v[208:209], v[150:151]
	v_fmac_f32_e32 v24, v146, v146
	v_fmac_f32_e32 v25, v144, v144
	v_add_f32_e32 v24, v24, v25
	v_mul_f32_e32 v25, v139, v139
	v_fmac_f32_e32 v25, v138, v138
	v_add_f32_e32 v24, v25, v24
	v_mul_f32_e32 v25, v137, v137
	v_fmac_f32_e32 v25, v136, v136
	v_add_f32_e32 v150, v25, v24
	v_lshlrev_b32_e32 v24, 16, v140
	v_and_b32_e32 v25, 0xffff0000, v140
	v_lshlrev_b32_e32 v26, 16, v141
	v_and_b32_e32 v27, 0xffff0000, v141
	v_pk_fma_f32 v[22:23], v[22:23], v[206:207], v[26:27]
	v_pk_fma_f32 v[20:21], v[20:21], v[204:205], v[24:25]
	v_lshlrev_b32_e32 v28, 16, v142
	v_and_b32_e32 v29, 0xffff0000, v142
	v_mul_f32_e32 v24, v21, v21
	v_mul_f32_e32 v25, v23, v23
	v_pk_fma_f32 v[16:17], v[16:17], v[200:201], v[28:29]
	v_fmac_f32_e32 v24, v20, v20
	v_fmac_f32_e32 v25, v22, v22
	v_lshlrev_b32_e32 v30, 16, v143
	v_and_b32_e32 v31, 0xffff0000, v143
	v_add_f32_e32 v24, v24, v25
	v_mul_f32_e32 v25, v17, v17
	v_pk_fma_f32 v[18:19], v[18:19], v[202:203], v[30:31]
	v_fmac_f32_e32 v25, v16, v16
	v_add_f32_e32 v24, v25, v24
	v_mul_f32_e32 v25, v19, v19
	v_fmac_f32_e32 v25, v18, v18
	v_add_f32_e32 v24, v25, v24
	v_add_f32_e32 v24, v150, v24
	ds_bpermute_b32 v25, v222, v24
	v_lshlrev_b64 v[154:155], 6, v[198:199]
	v_lshl_add_u64 v[150:151], v[154:155], 0, s[22:23]
	s_waitcnt lgkmcnt(0)
	v_add_f32_e32 v24, v24, v25
	ds_bpermute_b32 v25, v224, v24
	s_and_saveexec_b64 s[6:7], vcc
	s_cbranch_execz .LBB0_738
	s_waitcnt lgkmcnt(0)
	v_add_f32_e32 v26, v24, v25
	v_lshl_add_u64 v[24:25], s[30:31], 0, v[150:151]
	v_lshl_add_u64 v[24:25], s[0:1], 2, v[24:25]
	s_lshl_b32 s14, s81, 2
	v_lshl_add_u64 v[24:25], v[24:25], 0, s[14:15]
	s_cmp_eq_u32 s99, 1
	s_cbranch_scc1 .Lxp_plain_15
	global_store_dword v[24:25], v26, off sc1
	s_branch .Lxp_done_15
.Lxp_plain_15:
	global_store_dword v[24:25], v26, off
.Lxp_done_15:
.LBB0_738:
	s_or_b64 exec, exec, s[6:7]
	v_lshlrev_b32_e32 v24, 16, v128
	s_waitcnt lgkmcnt(0)
	v_and_b32_e32 v25, 0xffff0000, v128
	v_lshlrev_b32_e32 v26, 16, v129
	v_and_b32_e32 v27, 0xffff0000, v129
	v_lshlrev_b32_e32 v28, 16, v130
	v_and_b32_e32 v29, 0xffff0000, v130
	v_lshlrev_b32_e32 v30, 16, v131
	v_and_b32_e32 v31, 0xffff0000, v131
	v_pk_fma_f32 v[130:131], v[228:229], v[214:215], v[26:27]
	v_pk_fma_f32 v[142:143], v[226:227], v[212:213], v[24:25]
	v_mul_f32_e32 v9, v131, v131
	v_mul_f32_e32 v8, v143, v143
	v_pk_fma_f32 v[140:141], v[230:231], v[208:209], v[28:29]
	v_fmac_f32_e32 v8, v142, v142
	v_fmac_f32_e32 v9, v130, v130
	v_add_f32_e32 v8, v8, v9
	v_mul_f32_e32 v9, v141, v141
	v_pk_fma_f32 v[128:129], v[232:233], v[210:211], v[30:31]
	v_fmac_f32_e32 v9, v140, v140
	v_add_f32_e32 v8, v9, v8
	v_mul_f32_e32 v9, v129, v129
	v_fmac_f32_e32 v9, v128, v128
	v_add_f32_e32 v156, v9, v8
	v_lshlrev_b32_e32 v8, 16, v132
	v_and_b32_e32 v9, 0xffff0000, v132
	v_lshlrev_b32_e32 v10, 16, v133
	v_and_b32_e32 v11, 0xffff0000, v133
	v_lshlrev_b32_e32 v12, 16, v134
	v_and_b32_e32 v13, 0xffff0000, v134
	v_pk_fma_f32 v[26:27], v[6:7], v[206:207], v[10:11]
	v_pk_fma_f32 v[30:31], v[4:5], v[204:205], v[8:9]
	v_pk_fma_f32 v[28:29], v[0:1], v[200:201], v[12:13]
	v_mul_f32_e32 v0, v31, v31
	v_mul_f32_e32 v1, v27, v27
	v_fmac_f32_e32 v0, v30, v30
	v_fmac_f32_e32 v1, v26, v26
	v_lshlrev_b32_e32 v14, 16, v135
	v_and_b32_e32 v15, 0xffff0000, v135
	v_add_f32_e32 v0, v0, v1
	v_mul_f32_e32 v1, v29, v29
	v_pk_fma_f32 v[24:25], v[2:3], v[202:203], v[14:15]
	v_fmac_f32_e32 v1, v28, v28
	v_add_f32_e32 v0, v1, v0
	v_mul_f32_e32 v1, v25, v25
	v_fmac_f32_e32 v1, v24, v24
	v_add_f32_e32 v0, v1, v0
	v_add_f32_e32 v0, v156, v0
	ds_bpermute_b32 v1, v222, v0
	s_waitcnt lgkmcnt(0)
	v_add_f32_e32 v2, v0, v1
	ds_bpermute_b32 v3, v224, v2
	v_lshl_add_u64 v[0:1], v[154:155], 0, s[86:87]
	s_and_saveexec_b64 s[6:7], vcc
	s_cbranch_execz .LBB0_740
	s_waitcnt lgkmcnt(0)
	v_add_f32_e32 v4, v2, v3
	v_lshl_add_u64 v[2:3], s[30:31], 0, v[0:1]
	v_lshl_add_u64 v[2:3], s[0:1], 2, v[2:3]
	s_lshl_b32 s14, s81, 2
	v_lshl_add_u64 v[2:3], v[2:3], 0, s[14:15]
	s_cmp_eq_u32 s99, 1
	s_cbranch_scc1 .Lxp_plain_16
	global_store_dword v[2:3], v4, off sc1
	s_branch .Lxp_done_16
.Lxp_plain_16:
	global_store_dword v[2:3], v4, off
.Lxp_done_16:
.LBB0_740:
	s_or_b64 exec, exec, s[6:7]
	s_lshl_b32 s0, s34, 6
	s_ashr_i32 s1, s0, 31
	s_waitcnt vmcnt(0)
	s_lshl_b64 s[0:1], s[0:1], 2
	s_add_u32 s0, s75, s0
	s_addc_u32 s1, s76, s1
	s_and_saveexec_b64 s[6:7], s[2:3]
	s_cbranch_execz .LBB0_743
	s_cmp_eq_u32 s99, 1
	s_cbranch_scc0 .Lxs9_at
	s_lshr_b32 s14, s24, 6
	s_lshl_b32 s14, s14, 3
	s_add_i32 s14, s14, s32
	s_lshl_b32 s14, s14, 2
	s_lshl_b32 s98, s34, 7
	s_sub_i32 s98, 0x90000, s98
	s_add_i32 s14, s14, s98
	v_mov_b32_e32 v2, s14
	v_mov_b32_e32 v3, 1
	global_store_dword v2, v3, s[0:1]
	s_branch .LBB0_743
.Lxs9_at:
	s_mov_b64 s[34:35], exec
	v_mbcnt_lo_u32_b32 v2, s34, 0
	v_mbcnt_hi_u32_b32 v2, s35, v2
	v_cmp_eq_u32_e32 vcc, 0, v2
	s_and_b64 s[96:97], exec, vcc
	s_mov_b64 exec, s[96:97]
	s_cbranch_execz .LBB0_743
	s_bcnt1_i32_b64 s14, s[34:35]
	v_mov_b32_e32 v2, s14
	global_atomic_add v241, v2, s[0:1]
.LBB0_743:
	s_or_b64 exec, exec, s[6:7]
	s_mov_b64 s[6:7], exec
	v_readlane_b32 s34, v254, 10
	v_readlane_b32 s35, v254, 11
	s_and_b64 s[34:35], s[6:7], s[34:35]
	s_mov_b64 exec, s[34:35]
	s_cbranch_execz .LBB0_749
	s_cmp_eq_u32 s99, 1
	s_cbranch_scc0 .Lxs9_po
	v_mbcnt_lo_u32_b32 v2, -1, 0
	v_mbcnt_hi_u32_b32 v2, -1, v2
	v_and_b32_e32 v2, 31, v2
	v_lshlrev_b32_e32 v2, 2, v2
	v_add_u32_e32 v2, s98, v2
	s_mov_b32 s14, 0x100001
.Lxs9_spin:
	global_load_dword v3, v2, s[0:1] sc1
	s_waitcnt vmcnt(0)
	v_cmp_gt_u32_e32 vcc, 1, v3
	s_cbranch_vccz .LBB0_748
	s_add_i32 s14, s14, -1
	s_cmp_eq_u32 s14, 0
	s_cbranch_scc1 .LBB0_748
	s_sleep 1
	s_branch .Lxs9_spin
.Lxs9_po:
	s_mov_b32 s14, 0x100001
	s_branch .LBB0_746
